# GEMM K-loops: shorten the MFMA segment's critical path (s_setprio 1 before the barrier, drop satisfied lgkmcnt(0) after it, s_setprio 0 after the trailing barrier, drop mid-block flips)
# speedup vs baseline: 1.0153x; 1.0023x over previous
.LBB0_306:
	ds_read_b128 v[166:169], v162
	ds_read_b128 v[170:173], v162 offset:1024
	ds_read_b128 v[174:177], v162 offset:2048
	ds_read_b128 v[180:183], v162 offset:3072
	ds_read_b128 v[184:187], v163
	ds_read_b128 v[188:191], v163 offset:1024
	ds_read_b128 v[192:195], v163 offset:2048
	ds_read_b128 v[196:199], v163 offset:3072
	s_add_u32 s30, s28, 0xfff80080
	s_addc_u32 s31, s29, -1
	s_cmp_eq_u32 s50, 28
	s_cselect_b32 s35, s3, s31
	s_cselect_b32 s34, s21, s30
	s_cselect_b32 s31, s19, s49
	s_cselect_b32 s30, s27, s48
	v_lshl_add_u64 v[160:161], s[28:29], 0, v[152:153]
	s_add_i32 m0, s33, 0xc000
	ds_read_b128 v[200:203], v164
	ds_read_b128 v[204:207], v164 offset:1024
	ds_read_b128 v[208:211], v164 offset:2048
	ds_read_b128 v[212:215], v164 offset:3072
	ds_read_b128 v[216:219], v164 offset:4096
	ds_read_b128 v[220:223], v164 offset:5120
	ds_read_b128 v[224:227], v164 offset:6144
	ds_read_b128 v[228:231], v164 offset:7168
	global_load_lds_dwordx4 v[160:161], off
	v_lshl_add_u64 v[160:161], s[28:29], 0, v[154:155]
	s_add_i32 m0, s33, 0xe000
	s_nop 0
	global_load_lds_dwordx4 v[160:161], off
	s_waitcnt vmcnt(8)
	s_waitcnt lgkmcnt(0)
	s_setprio 1
	s_barrier
	v_mfma_f32_16x16x32_bf16 v[126:129], v[166:169], v[200:203], v[126:129]
	v_mfma_f32_16x16x32_bf16 v[122:125], v[174:177], v[200:203], v[122:125]
	v_mfma_f32_16x16x32_bf16 v[110:113], v[166:169], v[208:211], v[110:113]
	v_mfma_f32_16x16x32_bf16 v[106:109], v[174:177], v[208:211], v[106:109]
	v_mfma_f32_16x16x32_bf16 v[94:97], v[166:169], v[216:219], v[94:97]
	v_mfma_f32_16x16x32_bf16 v[90:93], v[174:177], v[216:219], v[90:93]
	v_mfma_f32_16x16x32_bf16 v[78:81], v[166:169], v[224:227], v[78:81]
	v_mfma_f32_16x16x32_bf16 v[74:77], v[174:177], v[224:227], v[74:77]
	v_mfma_f32_16x16x32_bf16 v[126:129], v[170:173], v[204:207], v[126:129]
	v_mfma_f32_16x16x32_bf16 v[122:125], v[180:183], v[204:207], v[122:125]
	v_mfma_f32_16x16x32_bf16 v[110:113], v[170:173], v[212:215], v[110:113]
	v_mfma_f32_16x16x32_bf16 v[106:109], v[180:183], v[212:215], v[106:109]
	v_mfma_f32_16x16x32_bf16 v[94:97], v[170:173], v[220:223], v[94:97]
	v_mfma_f32_16x16x32_bf16 v[90:93], v[180:183], v[220:223], v[90:93]
	v_mfma_f32_16x16x32_bf16 v[78:81], v[170:173], v[228:231], v[78:81]
	v_mfma_f32_16x16x32_bf16 v[74:77], v[180:183], v[228:231], v[74:77]
	v_mfma_f32_16x16x32_bf16 v[118:121], v[184:187], v[200:203], v[118:121]
	v_mfma_f32_16x16x32_bf16 v[114:117], v[192:195], v[200:203], v[114:117]
	v_mfma_f32_16x16x32_bf16 v[102:105], v[184:187], v[208:211], v[102:105]
	v_mfma_f32_16x16x32_bf16 v[98:101], v[192:195], v[208:211], v[98:101]
	v_mfma_f32_16x16x32_bf16 v[86:89], v[184:187], v[216:219], v[86:89]
	v_mfma_f32_16x16x32_bf16 v[82:85], v[192:195], v[216:219], v[82:85]
	v_mfma_f32_16x16x32_bf16 v[70:73], v[184:187], v[224:227], v[70:73]
	v_mfma_f32_16x16x32_bf16 v[66:69], v[192:195], v[224:227], v[66:69]
	v_mfma_f32_16x16x32_bf16 v[118:121], v[188:191], v[204:207], v[118:121]
	v_mfma_f32_16x16x32_bf16 v[114:117], v[196:199], v[204:207], v[114:117]
	v_mfma_f32_16x16x32_bf16 v[102:105], v[188:191], v[212:215], v[102:105]
	v_mfma_f32_16x16x32_bf16 v[98:101], v[196:199], v[212:215], v[98:101]
	v_mfma_f32_16x16x32_bf16 v[86:89], v[188:191], v[220:223], v[86:89]
	v_mfma_f32_16x16x32_bf16 v[82:85], v[196:199], v[220:223], v[82:85]
	v_mfma_f32_16x16x32_bf16 v[70:73], v[188:191], v[228:231], v[70:73]
	v_mfma_f32_16x16x32_bf16 v[66:69], v[196:199], v[228:231], v[66:69]
	s_barrier
	s_setprio 0
	s_add_i32 s51, s45, s17
	v_lshl_add_u64 v[160:161], s[30:31], 0, v[138:139]
	s_mov_b32 m0, s51
	ds_read_b128 v[200:203], v164 offset:16384
	ds_read_b128 v[204:207], v164 offset:17408
	ds_read_b128 v[208:211], v164 offset:18432
	ds_read_b128 v[212:215], v164 offset:19456
	ds_read_b128 v[216:219], v164 offset:20480
	ds_read_b128 v[220:223], v164 offset:21504
	ds_read_b128 v[224:227], v164 offset:22528
	ds_read_b128 v[228:231], v164 offset:23552
	global_load_lds_dwordx4 v[160:161], off
	s_add_i32 m0, s51, 0x2000
	s_add_u32 s56, s30, 0x80000
	v_lshl_add_u64 v[232:233], s[30:31], 0, v[142:143]
	s_addc_u32 s57, s31, 0
	s_add_i32 s51, s47, s17
	global_load_lds_dwordx4 v[232:233], off
	v_lshl_add_u64 v[234:235], s[56:57], 0, v[138:139]
	s_mov_b32 m0, s51
	v_lshl_add_u64 v[236:237], s[34:35], 0, v[140:141]
	global_load_lds_dwordx4 v[234:235], off
	v_lshl_add_u64 v[234:235], s[56:57], 0, v[142:143]
	s_add_i32 m0, s51, 0x2000
	s_nop 0
	global_load_lds_dwordx4 v[234:235], off
	v_lshl_add_u64 v[234:235], s[34:35], 0, v[136:137]
	s_mov_b32 m0, s33
	s_nop 0
	global_load_lds_dwordx4 v[234:235], off
	s_mov_b32 m0, s36
	s_nop 0
	global_load_lds_dwordx4 v[236:237], off
	s_waitcnt vmcnt(8)
	s_waitcnt lgkmcnt(0)
	s_setprio 1
	s_barrier
	v_mfma_f32_16x16x32_bf16 v[62:65], v[166:169], v[200:203], v[62:65]
	v_mfma_f32_16x16x32_bf16 v[58:61], v[174:177], v[200:203], v[58:61]
	v_mfma_f32_16x16x32_bf16 v[46:49], v[166:169], v[208:211], v[46:49]
	v_mfma_f32_16x16x32_bf16 v[42:45], v[174:177], v[208:211], v[42:45]
	v_mfma_f32_16x16x32_bf16 v[30:33], v[166:169], v[216:219], v[30:33]
	v_mfma_f32_16x16x32_bf16 v[26:29], v[174:177], v[216:219], v[26:29]
	v_mfma_f32_16x16x32_bf16 v[14:17], v[166:169], v[224:227], v[14:17]
	v_mfma_f32_16x16x32_bf16 v[10:13], v[174:177], v[224:227], v[10:13]
	v_mfma_f32_16x16x32_bf16 v[62:65], v[170:173], v[204:207], v[62:65]
	v_mfma_f32_16x16x32_bf16 v[58:61], v[180:183], v[204:207], v[58:61]
	v_mfma_f32_16x16x32_bf16 v[46:49], v[170:173], v[212:215], v[46:49]
	v_mfma_f32_16x16x32_bf16 v[42:45], v[180:183], v[212:215], v[42:45]
	v_mfma_f32_16x16x32_bf16 v[30:33], v[170:173], v[220:223], v[30:33]
	v_mfma_f32_16x16x32_bf16 v[26:29], v[180:183], v[220:223], v[26:29]
	v_mfma_f32_16x16x32_bf16 v[14:17], v[170:173], v[228:231], v[14:17]
	v_mfma_f32_16x16x32_bf16 v[10:13], v[180:183], v[228:231], v[10:13]
	v_mfma_f32_16x16x32_bf16 v[54:57], v[184:187], v[200:203], v[54:57]
	v_mfma_f32_16x16x32_bf16 v[50:53], v[192:195], v[200:203], v[50:53]
	v_mfma_f32_16x16x32_bf16 v[38:41], v[184:187], v[208:211], v[38:41]
	v_mfma_f32_16x16x32_bf16 v[34:37], v[192:195], v[208:211], v[34:37]
	v_mfma_f32_16x16x32_bf16 v[22:25], v[184:187], v[216:219], v[22:25]
	v_mfma_f32_16x16x32_bf16 v[18:21], v[192:195], v[216:219], v[18:21]
	v_mfma_f32_16x16x32_bf16 v[6:9], v[184:187], v[224:227], v[6:9]
	v_mfma_f32_16x16x32_bf16 v[2:5], v[192:195], v[224:227], v[2:5]
	v_mfma_f32_16x16x32_bf16 v[54:57], v[188:191], v[204:207], v[54:57]
	v_mfma_f32_16x16x32_bf16 v[50:53], v[196:199], v[204:207], v[50:53]
	v_mfma_f32_16x16x32_bf16 v[38:41], v[188:191], v[212:215], v[38:41]
	v_mfma_f32_16x16x32_bf16 v[34:37], v[196:199], v[212:215], v[34:37]
	v_mfma_f32_16x16x32_bf16 v[22:25], v[188:191], v[220:223], v[22:25]
	v_mfma_f32_16x16x32_bf16 v[18:21], v[196:199], v[220:223], v[18:21]
	v_mfma_f32_16x16x32_bf16 v[6:9], v[188:191], v[228:231], v[6:9]
	v_mfma_f32_16x16x32_bf16 v[2:5], v[196:199], v[228:231], v[2:5]
	s_barrier
	s_setprio 0
	s_add_i32 s51, 0, 0x18000
	v_add_u32_e32 v144, s51, v135
	s_add_i32 s56, 0, 0x1c000
	ds_read_b128 v[166:169], v144
	ds_read_b128 v[170:173], v144 offset:1024
	ds_read_b128 v[174:177], v144 offset:2048
	ds_read_b128 v[180:183], v144 offset:3072
	v_add_u32_e32 v144, s56, v135
	ds_read_b128 v[184:187], v144
	ds_read_b128 v[188:191], v144 offset:1024
	ds_read_b128 v[192:195], v144 offset:2048
	ds_read_b128 v[196:199], v144 offset:3072
	s_add_u32 s34, s34, 0x80000
	s_addc_u32 s35, s35, 0
	s_mov_b32 m0, s37
	v_lshl_add_u64 v[238:239], s[34:35], 0, v[136:137]
	ds_read_b128 v[200:203], v164 offset:32768
	ds_read_b128 v[204:207], v164 offset:33792
	ds_read_b128 v[208:211], v164 offset:34816
	ds_read_b128 v[212:215], v164 offset:35840
	ds_read_b128 v[216:219], v164 offset:36864
	ds_read_b128 v[220:223], v164 offset:37888
	ds_read_b128 v[224:227], v164 offset:38912
	ds_read_b128 v[228:231], v164 offset:39936
	global_load_lds_dwordx4 v[238:239], off
	v_lshl_add_u64 v[238:239], s[34:35], 0, v[140:141]
	s_mov_b32 m0, s38
	s_nop 0
	global_load_lds_dwordx4 v[238:239], off
	s_waitcnt vmcnt(8)
	s_waitcnt lgkmcnt(0)
	s_setprio 1
	s_barrier
	v_mfma_f32_16x16x32_bf16 v[126:129], v[166:169], v[200:203], v[126:129]
	v_mfma_f32_16x16x32_bf16 v[122:125], v[174:177], v[200:203], v[122:125]
	v_mfma_f32_16x16x32_bf16 v[110:113], v[166:169], v[208:211], v[110:113]
	v_mfma_f32_16x16x32_bf16 v[106:109], v[174:177], v[208:211], v[106:109]
	v_mfma_f32_16x16x32_bf16 v[94:97], v[166:169], v[216:219], v[94:97]
	v_mfma_f32_16x16x32_bf16 v[90:93], v[174:177], v[216:219], v[90:93]
	v_mfma_f32_16x16x32_bf16 v[78:81], v[166:169], v[224:227], v[78:81]
	v_mfma_f32_16x16x32_bf16 v[74:77], v[174:177], v[224:227], v[74:77]
	v_mfma_f32_16x16x32_bf16 v[126:129], v[170:173], v[204:207], v[126:129]
	v_mfma_f32_16x16x32_bf16 v[122:125], v[180:183], v[204:207], v[122:125]
	v_mfma_f32_16x16x32_bf16 v[110:113], v[170:173], v[212:215], v[110:113]
	v_mfma_f32_16x16x32_bf16 v[106:109], v[180:183], v[212:215], v[106:109]
	v_mfma_f32_16x16x32_bf16 v[94:97], v[170:173], v[220:223], v[94:97]
	v_mfma_f32_16x16x32_bf16 v[90:93], v[180:183], v[220:223], v[90:93]
	v_mfma_f32_16x16x32_bf16 v[78:81], v[170:173], v[228:231], v[78:81]
	v_mfma_f32_16x16x32_bf16 v[74:77], v[180:183], v[228:231], v[74:77]
	v_mfma_f32_16x16x32_bf16 v[118:121], v[184:187], v[200:203], v[118:121]
	v_mfma_f32_16x16x32_bf16 v[114:117], v[192:195], v[200:203], v[114:117]
	v_mfma_f32_16x16x32_bf16 v[102:105], v[184:187], v[208:211], v[102:105]
	v_mfma_f32_16x16x32_bf16 v[98:101], v[192:195], v[208:211], v[98:101]
	v_mfma_f32_16x16x32_bf16 v[86:89], v[184:187], v[216:219], v[86:89]
	v_mfma_f32_16x16x32_bf16 v[82:85], v[192:195], v[216:219], v[82:85]
	v_mfma_f32_16x16x32_bf16 v[70:73], v[184:187], v[224:227], v[70:73]
	v_mfma_f32_16x16x32_bf16 v[66:69], v[192:195], v[224:227], v[66:69]
	v_mfma_f32_16x16x32_bf16 v[118:121], v[188:191], v[204:207], v[118:121]
	v_mfma_f32_16x16x32_bf16 v[114:117], v[196:199], v[204:207], v[114:117]
	v_mfma_f32_16x16x32_bf16 v[102:105], v[188:191], v[212:215], v[102:105]
	v_mfma_f32_16x16x32_bf16 v[98:101], v[196:199], v[212:215], v[98:101]
	v_mfma_f32_16x16x32_bf16 v[86:89], v[188:191], v[220:223], v[86:89]
	v_mfma_f32_16x16x32_bf16 v[82:85], v[196:199], v[220:223], v[82:85]
	v_mfma_f32_16x16x32_bf16 v[70:73], v[188:191], v[228:231], v[70:73]
	v_mfma_f32_16x16x32_bf16 v[66:69], v[196:199], v[228:231], v[66:69]
	s_barrier
	s_setprio 0
	s_add_i32 s34, s51, s17
	v_lshl_add_u64 v[160:161], v[160:161], 0, s[6:7]
	s_mov_b32 m0, s34
	ds_read_b128 v[200:203], v164 offset:49152
	ds_read_b128 v[204:207], v164 offset:50176
	ds_read_b128 v[208:211], v164 offset:51200
	ds_read_b128 v[212:215], v164 offset:52224
	ds_read_b128 v[216:219], v164 offset:53248
	ds_read_b128 v[220:223], v164 offset:54272
	ds_read_b128 v[224:227], v164 offset:55296
	ds_read_b128 v[228:231], v164 offset:56320
	global_load_lds_dwordx4 v[160:161], off
	s_add_i32 m0, s34, 0x2000
	s_add_u32 s30, s30, 0x80080
	v_lshl_add_u64 v[160:161], v[232:233], 0, s[6:7]
	s_addc_u32 s31, s31, 0
	s_add_i32 s34, s56, s17
	global_load_lds_dwordx4 v[160:161], off
	v_lshl_add_u64 v[160:161], s[30:31], 0, v[138:139]
	s_mov_b32 m0, s34
	s_nop 0
	global_load_lds_dwordx4 v[160:161], off
	v_lshl_add_u64 v[160:161], s[30:31], 0, v[142:143]
	s_add_i32 m0, s34, 0x2000
	s_nop 0
	global_load_lds_dwordx4 v[160:161], off
	v_lshl_add_u64 v[160:161], v[234:235], 0, s[6:7]
	s_mov_b32 m0, s40
	s_nop 0
	global_load_lds_dwordx4 v[160:161], off
	v_lshl_add_u64 v[160:161], v[236:237], 0, s[6:7]
	s_mov_b32 m0, s41
	s_nop 0
	global_load_lds_dwordx4 v[160:161], off
	s_waitcnt vmcnt(8)
	s_waitcnt lgkmcnt(0)
	s_setprio 1
	s_barrier
	v_mfma_f32_16x16x32_bf16 v[62:65], v[166:169], v[200:203], v[62:65]
	v_mfma_f32_16x16x32_bf16 v[58:61], v[174:177], v[200:203], v[58:61]
	v_mfma_f32_16x16x32_bf16 v[46:49], v[166:169], v[208:211], v[46:49]
	v_mfma_f32_16x16x32_bf16 v[42:45], v[174:177], v[208:211], v[42:45]
	v_mfma_f32_16x16x32_bf16 v[30:33], v[166:169], v[216:219], v[30:33]
	v_mfma_f32_16x16x32_bf16 v[26:29], v[174:177], v[216:219], v[26:29]
	v_mfma_f32_16x16x32_bf16 v[14:17], v[166:169], v[224:227], v[14:17]
	v_mfma_f32_16x16x32_bf16 v[10:13], v[174:177], v[224:227], v[10:13]
	v_mfma_f32_16x16x32_bf16 v[62:65], v[170:173], v[204:207], v[62:65]
	v_mfma_f32_16x16x32_bf16 v[58:61], v[180:183], v[204:207], v[58:61]
	v_mfma_f32_16x16x32_bf16 v[46:49], v[170:173], v[212:215], v[46:49]
	v_mfma_f32_16x16x32_bf16 v[42:45], v[180:183], v[212:215], v[42:45]
	v_mfma_f32_16x16x32_bf16 v[30:33], v[170:173], v[220:223], v[30:33]
	v_mfma_f32_16x16x32_bf16 v[26:29], v[180:183], v[220:223], v[26:29]
	v_mfma_f32_16x16x32_bf16 v[14:17], v[170:173], v[228:231], v[14:17]
	v_mfma_f32_16x16x32_bf16 v[10:13], v[180:183], v[228:231], v[10:13]
	v_mfma_f32_16x16x32_bf16 v[54:57], v[184:187], v[200:203], v[54:57]
	v_mfma_f32_16x16x32_bf16 v[50:53], v[192:195], v[200:203], v[50:53]
	v_mfma_f32_16x16x32_bf16 v[38:41], v[184:187], v[208:211], v[38:41]
	v_mfma_f32_16x16x32_bf16 v[34:37], v[192:195], v[208:211], v[34:37]
	v_mfma_f32_16x16x32_bf16 v[22:25], v[184:187], v[216:219], v[22:25]
	v_mfma_f32_16x16x32_bf16 v[18:21], v[192:195], v[216:219], v[18:21]
	v_mfma_f32_16x16x32_bf16 v[6:9], v[184:187], v[224:227], v[6:9]
	v_mfma_f32_16x16x32_bf16 v[2:5], v[192:195], v[224:227], v[2:5]
	v_mfma_f32_16x16x32_bf16 v[54:57], v[188:191], v[204:207], v[54:57]
	v_mfma_f32_16x16x32_bf16 v[50:53], v[196:199], v[204:207], v[50:53]
	v_mfma_f32_16x16x32_bf16 v[38:41], v[188:191], v[212:215], v[38:41]
	v_mfma_f32_16x16x32_bf16 v[34:37], v[196:199], v[212:215], v[34:37]
	v_mfma_f32_16x16x32_bf16 v[22:25], v[188:191], v[220:223], v[22:25]
	v_mfma_f32_16x16x32_bf16 v[18:21], v[196:199], v[220:223], v[18:21]
	v_mfma_f32_16x16x32_bf16 v[6:9], v[188:191], v[228:231], v[6:9]
	v_mfma_f32_16x16x32_bf16 v[2:5], v[196:199], v[228:231], v[2:5]
	s_barrier
	s_setprio 0
	s_add_i32 s50, s50, 2
	s_add_u32 s28, s28, 0x100
	s_addc_u32 s29, s29, 0
	s_add_u32 s48, s48, 0x100
	s_addc_u32 s49, s49, 0
	s_cmp_gt_u32 s50, 29
	s_cbranch_scc0 .LBB0_306
	s_and_b64 vcc, exec, s[8:9]
	s_cbranch_vccz .LBB0_314
	s_barrier
	v_lshl_add_u32 v160, s26, 8, v133
	s_cmp_gt_i32 s2, 35
	s_mov_b64 s[26:27], -1
	s_cbranch_scc1 .LBB0_315

.LBB0_986:
	ds_read_b128 v[148:151], v155
	ds_read_b128 v[158:161], v155 offset:1024
	ds_read_b128 v[162:165], v155 offset:2048
	ds_read_b128 v[166:169], v155 offset:3072
	ds_read_b128 v[170:173], v156
	ds_read_b128 v[174:177], v156 offset:1024
	ds_read_b128 v[180:183], v156 offset:2048
	ds_read_b128 v[184:187], v156 offset:3072
	s_add_u32 s26, s24, 0xfffc0080
	s_addc_u32 s27, s25, -1
	s_cmp_eq_u32 s49, 12
	s_cselect_b32 s29, s17, s27
	s_cselect_b32 s28, s45, s26
	s_cselect_b32 s27, s15, s48
	s_cselect_b32 s26, s46, s47
	v_lshl_add_u64 v[220:221], s[24:25], 0, v[138:139]
	s_add_i32 m0, s23, 0xc000
	ds_read_b128 v[188:191], v157
	ds_read_b128 v[192:195], v157 offset:1024
	ds_read_b128 v[196:199], v157 offset:2048
	ds_read_b128 v[200:203], v157 offset:3072
	ds_read_b128 v[204:207], v157 offset:4096
	ds_read_b128 v[208:211], v157 offset:5120
	ds_read_b128 v[212:215], v157 offset:6144
	ds_read_b128 v[216:219], v157 offset:7168
	global_load_lds_dwordx4 v[220:221], off
	v_lshl_add_u64 v[220:221], s[24:25], 0, v[140:141]
	s_add_i32 m0, s23, 0xe000
	s_nop 0
	global_load_lds_dwordx4 v[220:221], off
	s_waitcnt vmcnt(8)
	s_waitcnt lgkmcnt(0)
	s_setprio 1
	s_barrier
	v_mfma_f32_16x16x32_bf16 v[126:129], v[148:151], v[188:191], v[126:129]
	v_mfma_f32_16x16x32_bf16 v[122:125], v[162:165], v[188:191], v[122:125]
	v_mfma_f32_16x16x32_bf16 v[110:113], v[148:151], v[196:199], v[110:113]
	v_mfma_f32_16x16x32_bf16 v[106:109], v[162:165], v[196:199], v[106:109]
	v_mfma_f32_16x16x32_bf16 v[94:97], v[148:151], v[204:207], v[94:97]
	v_mfma_f32_16x16x32_bf16 v[90:93], v[162:165], v[204:207], v[90:93]
	v_mfma_f32_16x16x32_bf16 v[78:81], v[148:151], v[212:215], v[78:81]
	v_mfma_f32_16x16x32_bf16 v[74:77], v[162:165], v[212:215], v[74:77]
	v_mfma_f32_16x16x32_bf16 v[126:129], v[158:161], v[192:195], v[126:129]
	v_mfma_f32_16x16x32_bf16 v[122:125], v[166:169], v[192:195], v[122:125]
	v_mfma_f32_16x16x32_bf16 v[110:113], v[158:161], v[200:203], v[110:113]
	v_mfma_f32_16x16x32_bf16 v[106:109], v[166:169], v[200:203], v[106:109]
	v_mfma_f32_16x16x32_bf16 v[94:97], v[158:161], v[208:211], v[94:97]
	v_mfma_f32_16x16x32_bf16 v[90:93], v[166:169], v[208:211], v[90:93]
	v_mfma_f32_16x16x32_bf16 v[78:81], v[158:161], v[216:219], v[78:81]
	v_mfma_f32_16x16x32_bf16 v[74:77], v[166:169], v[216:219], v[74:77]
	v_mfma_f32_16x16x32_bf16 v[118:121], v[170:173], v[188:191], v[118:121]
	v_mfma_f32_16x16x32_bf16 v[114:117], v[180:183], v[188:191], v[114:117]
	v_mfma_f32_16x16x32_bf16 v[102:105], v[170:173], v[196:199], v[102:105]
	v_mfma_f32_16x16x32_bf16 v[98:101], v[180:183], v[196:199], v[98:101]
	v_mfma_f32_16x16x32_bf16 v[86:89], v[170:173], v[204:207], v[86:89]
	v_mfma_f32_16x16x32_bf16 v[82:85], v[180:183], v[204:207], v[82:85]
	v_mfma_f32_16x16x32_bf16 v[70:73], v[170:173], v[212:215], v[70:73]
	v_mfma_f32_16x16x32_bf16 v[66:69], v[180:183], v[212:215], v[66:69]
	v_mfma_f32_16x16x32_bf16 v[118:121], v[174:177], v[192:195], v[118:121]
	v_mfma_f32_16x16x32_bf16 v[114:117], v[184:187], v[192:195], v[114:117]
	v_mfma_f32_16x16x32_bf16 v[102:105], v[174:177], v[200:203], v[102:105]
	v_mfma_f32_16x16x32_bf16 v[98:101], v[184:187], v[200:203], v[98:101]
	v_mfma_f32_16x16x32_bf16 v[86:89], v[174:177], v[208:211], v[86:89]
	v_mfma_f32_16x16x32_bf16 v[82:85], v[184:187], v[208:211], v[82:85]
	v_mfma_f32_16x16x32_bf16 v[70:73], v[174:177], v[216:219], v[70:73]
	v_mfma_f32_16x16x32_bf16 v[66:69], v[184:187], v[216:219], v[66:69]
	s_barrier
	s_setprio 0
	s_add_i32 s50, s42, s30
	v_lshl_add_u64 v[220:221], s[26:27], 0, v[134:135]
	s_mov_b32 m0, s50
	ds_read_b128 v[188:191], v157 offset:16384
	ds_read_b128 v[192:195], v157 offset:17408
	ds_read_b128 v[196:199], v157 offset:18432
	ds_read_b128 v[200:203], v157 offset:19456
	ds_read_b128 v[204:207], v157 offset:20480
	ds_read_b128 v[208:211], v157 offset:21504
	ds_read_b128 v[212:215], v157 offset:22528
	ds_read_b128 v[216:219], v157 offset:23552
	global_load_lds_dwordx4 v[220:221], off
	s_add_i32 m0, s50, 0x2000
	s_add_u32 s50, s26, 0x40000
	v_lshl_add_u64 v[222:223], s[26:27], 0, v[130:131]
	s_addc_u32 s51, s27, 0
	s_add_i32 s56, s43, s30
	global_load_lds_dwordx4 v[222:223], off
	v_lshl_add_u64 v[224:225], s[50:51], 0, v[134:135]
	s_mov_b32 m0, s56
	v_lshl_add_u64 v[226:227], s[28:29], 0, v[132:133]
	global_load_lds_dwordx4 v[224:225], off
	v_lshl_add_u64 v[224:225], s[50:51], 0, v[130:131]
	s_add_i32 m0, s56, 0x2000
	s_nop 0
	global_load_lds_dwordx4 v[224:225], off
	v_lshl_add_u64 v[224:225], s[28:29], 0, v[136:137]
	s_mov_b32 m0, s23
	s_nop 0
	global_load_lds_dwordx4 v[224:225], off
	s_mov_b32 m0, s34
	s_nop 0
	global_load_lds_dwordx4 v[226:227], off
	s_waitcnt vmcnt(8)
	s_waitcnt lgkmcnt(0)
	s_setprio 1
	s_barrier
	v_mfma_f32_16x16x32_bf16 v[62:65], v[148:151], v[188:191], v[62:65]
	v_mfma_f32_16x16x32_bf16 v[58:61], v[162:165], v[188:191], v[58:61]
	v_mfma_f32_16x16x32_bf16 v[46:49], v[148:151], v[196:199], v[46:49]
	v_mfma_f32_16x16x32_bf16 v[42:45], v[162:165], v[196:199], v[42:45]
	v_mfma_f32_16x16x32_bf16 v[30:33], v[148:151], v[204:207], v[30:33]
	v_mfma_f32_16x16x32_bf16 v[26:29], v[162:165], v[204:207], v[26:29]
	v_mfma_f32_16x16x32_bf16 v[14:17], v[148:151], v[212:215], v[14:17]
	v_mfma_f32_16x16x32_bf16 v[10:13], v[162:165], v[212:215], v[10:13]
	v_mfma_f32_16x16x32_bf16 v[62:65], v[158:161], v[192:195], v[62:65]
	v_mfma_f32_16x16x32_bf16 v[58:61], v[166:169], v[192:195], v[58:61]
	v_mfma_f32_16x16x32_bf16 v[46:49], v[158:161], v[200:203], v[46:49]
	v_mfma_f32_16x16x32_bf16 v[42:45], v[166:169], v[200:203], v[42:45]
	v_mfma_f32_16x16x32_bf16 v[30:33], v[158:161], v[208:211], v[30:33]
	v_mfma_f32_16x16x32_bf16 v[26:29], v[166:169], v[208:211], v[26:29]
	v_mfma_f32_16x16x32_bf16 v[14:17], v[158:161], v[216:219], v[14:17]
	v_mfma_f32_16x16x32_bf16 v[10:13], v[166:169], v[216:219], v[10:13]
	v_mfma_f32_16x16x32_bf16 v[54:57], v[170:173], v[188:191], v[54:57]
	v_mfma_f32_16x16x32_bf16 v[50:53], v[180:183], v[188:191], v[50:53]
	v_mfma_f32_16x16x32_bf16 v[38:41], v[170:173], v[196:199], v[38:41]
	v_mfma_f32_16x16x32_bf16 v[34:37], v[180:183], v[196:199], v[34:37]
	v_mfma_f32_16x16x32_bf16 v[22:25], v[170:173], v[204:207], v[22:25]
	v_mfma_f32_16x16x32_bf16 v[18:21], v[180:183], v[204:207], v[18:21]
	v_mfma_f32_16x16x32_bf16 v[6:9], v[170:173], v[212:215], v[6:9]
	v_mfma_f32_16x16x32_bf16 v[2:5], v[180:183], v[212:215], v[2:5]
	v_mfma_f32_16x16x32_bf16 v[54:57], v[174:177], v[192:195], v[54:57]
	v_mfma_f32_16x16x32_bf16 v[50:53], v[184:187], v[192:195], v[50:53]
	v_mfma_f32_16x16x32_bf16 v[38:41], v[174:177], v[200:203], v[38:41]
	v_mfma_f32_16x16x32_bf16 v[34:37], v[184:187], v[200:203], v[34:37]
	v_mfma_f32_16x16x32_bf16 v[22:25], v[174:177], v[208:211], v[22:25]
	v_mfma_f32_16x16x32_bf16 v[18:21], v[184:187], v[208:211], v[18:21]
	v_mfma_f32_16x16x32_bf16 v[6:9], v[174:177], v[216:219], v[6:9]
	v_mfma_f32_16x16x32_bf16 v[2:5], v[184:187], v[216:219], v[2:5]
	s_barrier
	s_setprio 0
	s_add_i32 s50, 0, 0x18000
	s_add_i32 s51, 0, 0x1c000
	v_add_u32_e32 v166, s50, v153
	v_add_u32_e32 v179, s51, v153
	ds_read_b128 v[148:151], v166
	ds_read_b128 v[158:161], v166 offset:1024
	ds_read_b128 v[162:165], v166 offset:2048
	ds_read_b128 v[166:169], v166 offset:3072
	ds_read_b128 v[170:173], v179
	ds_read_b128 v[174:177], v179 offset:1024
	ds_read_b128 v[180:183], v179 offset:2048
	ds_read_b128 v[184:187], v179 offset:3072
	s_add_u32 s28, s28, 0x40000
	s_addc_u32 s29, s29, 0
	s_mov_b32 m0, s35
	v_lshl_add_u64 v[228:229], s[28:29], 0, v[136:137]
	ds_read_b128 v[188:191], v157 offset:32768
	ds_read_b128 v[192:195], v157 offset:33792
	ds_read_b128 v[196:199], v157 offset:34816
	ds_read_b128 v[200:203], v157 offset:35840
	ds_read_b128 v[204:207], v157 offset:36864
	ds_read_b128 v[208:211], v157 offset:37888
	ds_read_b128 v[212:215], v157 offset:38912
	ds_read_b128 v[216:219], v157 offset:39936
	global_load_lds_dwordx4 v[228:229], off
	v_lshl_add_u64 v[228:229], s[28:29], 0, v[132:133]
	s_mov_b32 m0, s36
	s_nop 0
	global_load_lds_dwordx4 v[228:229], off
	s_waitcnt vmcnt(8)
	s_waitcnt lgkmcnt(0)
	s_setprio 1
	s_barrier
	v_mfma_f32_16x16x32_bf16 v[126:129], v[148:151], v[188:191], v[126:129]
	v_mfma_f32_16x16x32_bf16 v[122:125], v[162:165], v[188:191], v[122:125]
	v_mfma_f32_16x16x32_bf16 v[110:113], v[148:151], v[196:199], v[110:113]
	v_mfma_f32_16x16x32_bf16 v[106:109], v[162:165], v[196:199], v[106:109]
	v_mfma_f32_16x16x32_bf16 v[94:97], v[148:151], v[204:207], v[94:97]
	v_mfma_f32_16x16x32_bf16 v[90:93], v[162:165], v[204:207], v[90:93]
	v_mfma_f32_16x16x32_bf16 v[78:81], v[148:151], v[212:215], v[78:81]
	v_mfma_f32_16x16x32_bf16 v[74:77], v[162:165], v[212:215], v[74:77]
	v_mfma_f32_16x16x32_bf16 v[126:129], v[158:161], v[192:195], v[126:129]
	v_mfma_f32_16x16x32_bf16 v[122:125], v[166:169], v[192:195], v[122:125]
	v_mfma_f32_16x16x32_bf16 v[110:113], v[158:161], v[200:203], v[110:113]
	v_mfma_f32_16x16x32_bf16 v[106:109], v[166:169], v[200:203], v[106:109]
	v_mfma_f32_16x16x32_bf16 v[94:97], v[158:161], v[208:211], v[94:97]
	v_mfma_f32_16x16x32_bf16 v[90:93], v[166:169], v[208:211], v[90:93]
	v_mfma_f32_16x16x32_bf16 v[78:81], v[158:161], v[216:219], v[78:81]
	v_mfma_f32_16x16x32_bf16 v[74:77], v[166:169], v[216:219], v[74:77]
	v_mfma_f32_16x16x32_bf16 v[118:121], v[170:173], v[188:191], v[118:121]
	v_mfma_f32_16x16x32_bf16 v[114:117], v[180:183], v[188:191], v[114:117]
	v_mfma_f32_16x16x32_bf16 v[102:105], v[170:173], v[196:199], v[102:105]
	v_mfma_f32_16x16x32_bf16 v[98:101], v[180:183], v[196:199], v[98:101]
	v_mfma_f32_16x16x32_bf16 v[86:89], v[170:173], v[204:207], v[86:89]
	v_mfma_f32_16x16x32_bf16 v[82:85], v[180:183], v[204:207], v[82:85]
	v_mfma_f32_16x16x32_bf16 v[70:73], v[170:173], v[212:215], v[70:73]
	v_mfma_f32_16x16x32_bf16 v[66:69], v[180:183], v[212:215], v[66:69]
	v_mfma_f32_16x16x32_bf16 v[118:121], v[174:177], v[192:195], v[118:121]
	v_mfma_f32_16x16x32_bf16 v[114:117], v[184:187], v[192:195], v[114:117]
	v_mfma_f32_16x16x32_bf16 v[102:105], v[174:177], v[200:203], v[102:105]
	v_mfma_f32_16x16x32_bf16 v[98:101], v[184:187], v[200:203], v[98:101]
	v_mfma_f32_16x16x32_bf16 v[86:89], v[174:177], v[208:211], v[86:89]
	v_mfma_f32_16x16x32_bf16 v[82:85], v[184:187], v[208:211], v[82:85]
	v_mfma_f32_16x16x32_bf16 v[70:73], v[174:177], v[216:219], v[70:73]
	v_mfma_f32_16x16x32_bf16 v[66:69], v[184:187], v[216:219], v[66:69]
	s_barrier
	s_setprio 0
	s_add_i32 s28, s50, s30
	v_lshl_add_u64 v[220:221], v[220:221], 0, s[4:5]
	s_mov_b32 m0, s28
	ds_read_b128 v[188:191], v157 offset:49152
	ds_read_b128 v[192:195], v157 offset:50176
	ds_read_b128 v[196:199], v157 offset:51200
	ds_read_b128 v[200:203], v157 offset:52224
	ds_read_b128 v[204:207], v157 offset:53248
	ds_read_b128 v[208:211], v157 offset:54272
	ds_read_b128 v[212:215], v157 offset:55296
	ds_read_b128 v[216:219], v157 offset:56320
	global_load_lds_dwordx4 v[220:221], off
	s_add_i32 m0, s28, 0x2000
	s_add_u32 s26, s26, 0x40080
	v_lshl_add_u64 v[220:221], v[222:223], 0, s[4:5]
	s_addc_u32 s27, s27, 0
	s_add_i32 s28, s51, s30
	global_load_lds_dwordx4 v[220:221], off
	v_lshl_add_u64 v[220:221], s[26:27], 0, v[134:135]
	s_mov_b32 m0, s28
	s_nop 0
	global_load_lds_dwordx4 v[220:221], off
	v_lshl_add_u64 v[220:221], s[26:27], 0, v[130:131]
	s_add_i32 m0, s28, 0x2000
	s_nop 0
	global_load_lds_dwordx4 v[220:221], off
	v_lshl_add_u64 v[220:221], v[224:225], 0, s[4:5]
	s_mov_b32 m0, s38
	s_nop 0
	global_load_lds_dwordx4 v[220:221], off
	v_lshl_add_u64 v[220:221], v[226:227], 0, s[4:5]
	s_mov_b32 m0, s39
	s_nop 0
	global_load_lds_dwordx4 v[220:221], off
	s_waitcnt vmcnt(8)
	s_waitcnt lgkmcnt(0)
	s_setprio 1
	s_barrier
	v_mfma_f32_16x16x32_bf16 v[62:65], v[148:151], v[188:191], v[62:65]
	v_mfma_f32_16x16x32_bf16 v[58:61], v[162:165], v[188:191], v[58:61]
	v_mfma_f32_16x16x32_bf16 v[46:49], v[148:151], v[196:199], v[46:49]
	v_mfma_f32_16x16x32_bf16 v[42:45], v[162:165], v[196:199], v[42:45]
	v_mfma_f32_16x16x32_bf16 v[30:33], v[148:151], v[204:207], v[30:33]
	v_mfma_f32_16x16x32_bf16 v[26:29], v[162:165], v[204:207], v[26:29]
	v_mfma_f32_16x16x32_bf16 v[14:17], v[148:151], v[212:215], v[14:17]
	v_mfma_f32_16x16x32_bf16 v[10:13], v[162:165], v[212:215], v[10:13]
	v_mfma_f32_16x16x32_bf16 v[62:65], v[158:161], v[192:195], v[62:65]
	v_mfma_f32_16x16x32_bf16 v[58:61], v[166:169], v[192:195], v[58:61]
	v_mfma_f32_16x16x32_bf16 v[46:49], v[158:161], v[200:203], v[46:49]
	v_mfma_f32_16x16x32_bf16 v[42:45], v[166:169], v[200:203], v[42:45]
	v_mfma_f32_16x16x32_bf16 v[30:33], v[158:161], v[208:211], v[30:33]
	v_mfma_f32_16x16x32_bf16 v[26:29], v[166:169], v[208:211], v[26:29]
	v_mfma_f32_16x16x32_bf16 v[14:17], v[158:161], v[216:219], v[14:17]
	v_mfma_f32_16x16x32_bf16 v[10:13], v[166:169], v[216:219], v[10:13]
	v_mfma_f32_16x16x32_bf16 v[54:57], v[170:173], v[188:191], v[54:57]
	v_mfma_f32_16x16x32_bf16 v[50:53], v[180:183], v[188:191], v[50:53]
	v_mfma_f32_16x16x32_bf16 v[38:41], v[170:173], v[196:199], v[38:41]
	v_mfma_f32_16x16x32_bf16 v[34:37], v[180:183], v[196:199], v[34:37]
	v_mfma_f32_16x16x32_bf16 v[22:25], v[170:173], v[204:207], v[22:25]
	v_mfma_f32_16x16x32_bf16 v[18:21], v[180:183], v[204:207], v[18:21]
	v_mfma_f32_16x16x32_bf16 v[6:9], v[170:173], v[212:215], v[6:9]
	v_mfma_f32_16x16x32_bf16 v[2:5], v[180:183], v[212:215], v[2:5]
	v_mfma_f32_16x16x32_bf16 v[54:57], v[174:177], v[192:195], v[54:57]
	v_mfma_f32_16x16x32_bf16 v[50:53], v[184:187], v[192:195], v[50:53]
	v_mfma_f32_16x16x32_bf16 v[38:41], v[174:177], v[200:203], v[38:41]
	v_mfma_f32_16x16x32_bf16 v[34:37], v[184:187], v[200:203], v[34:37]
	v_mfma_f32_16x16x32_bf16 v[22:25], v[174:177], v[208:211], v[22:25]
	v_mfma_f32_16x16x32_bf16 v[18:21], v[184:187], v[208:211], v[18:21]
	v_mfma_f32_16x16x32_bf16 v[6:9], v[174:177], v[216:219], v[6:9]
	v_mfma_f32_16x16x32_bf16 v[2:5], v[184:187], v[216:219], v[2:5]
	s_barrier
	s_setprio 0
	s_add_i32 s49, s49, 2
	s_add_u32 s24, s24, 0x100
	s_addc_u32 s25, s25, 0
	s_add_u32 s47, s47, 0x100
	s_addc_u32 s48, s48, 0
	s_cmp_gt_u32 s49, 13
	s_cbranch_scc0 .LBB0_986
	s_and_b64 vcc, exec, s[8:9]
	s_cbranch_vccz .LBB0_989
	s_barrier

.LBB0_1054:
	ds_read_b128 v[148:151], v155
	ds_read_b128 v[158:161], v155 offset:1024
	ds_read_b128 v[162:165], v155 offset:2048
	ds_read_b128 v[166:169], v155 offset:3072
	ds_read_b128 v[170:173], v156
	ds_read_b128 v[174:177], v156 offset:1024
	ds_read_b128 v[180:183], v156 offset:2048
	ds_read_b128 v[184:187], v156 offset:3072
	s_add_u32 s26, s24, 0xfffc0080
	s_addc_u32 s27, s25, -1
	s_cmp_eq_u32 s50, 12
	s_cselect_b32 s29, s17, s27
	s_cselect_b32 s28, s46, s26
	s_cselect_b32 s27, s15, s49
	s_cselect_b32 s26, s47, s48
	v_lshl_add_u64 v[220:221], s[24:25], 0, v[138:139]
	s_add_i32 m0, s23, 0xc000
	ds_read_b128 v[188:191], v157
	ds_read_b128 v[192:195], v157 offset:1024
	ds_read_b128 v[196:199], v157 offset:2048
	ds_read_b128 v[200:203], v157 offset:3072
	ds_read_b128 v[204:207], v157 offset:4096
	ds_read_b128 v[208:211], v157 offset:5120
	ds_read_b128 v[212:215], v157 offset:6144
	ds_read_b128 v[216:219], v157 offset:7168
	global_load_lds_dwordx4 v[220:221], off
	v_lshl_add_u64 v[220:221], s[24:25], 0, v[140:141]
	s_add_i32 m0, s23, 0xe000
	s_nop 0
	global_load_lds_dwordx4 v[220:221], off
	s_waitcnt vmcnt(8)
	s_waitcnt lgkmcnt(0)
	s_setprio 1
	s_barrier
	v_mfma_f32_16x16x32_bf16 v[118:121], v[148:151], v[188:191], v[118:121]
	v_mfma_f32_16x16x32_bf16 v[114:117], v[162:165], v[188:191], v[114:117]
	v_mfma_f32_16x16x32_bf16 v[102:105], v[148:151], v[196:199], v[102:105]
	v_mfma_f32_16x16x32_bf16 v[98:101], v[162:165], v[196:199], v[98:101]
	v_mfma_f32_16x16x32_bf16 v[86:89], v[148:151], v[204:207], v[86:89]
	v_mfma_f32_16x16x32_bf16 v[82:85], v[162:165], v[204:207], v[82:85]
	v_mfma_f32_16x16x32_bf16 v[70:73], v[148:151], v[212:215], v[70:73]
	v_mfma_f32_16x16x32_bf16 v[66:69], v[162:165], v[212:215], v[66:69]
	v_mfma_f32_16x16x32_bf16 v[118:121], v[158:161], v[192:195], v[118:121]
	v_mfma_f32_16x16x32_bf16 v[114:117], v[166:169], v[192:195], v[114:117]
	v_mfma_f32_16x16x32_bf16 v[102:105], v[158:161], v[200:203], v[102:105]
	v_mfma_f32_16x16x32_bf16 v[98:101], v[166:169], v[200:203], v[98:101]
	v_mfma_f32_16x16x32_bf16 v[86:89], v[158:161], v[208:211], v[86:89]
	v_mfma_f32_16x16x32_bf16 v[82:85], v[166:169], v[208:211], v[82:85]
	v_mfma_f32_16x16x32_bf16 v[70:73], v[158:161], v[216:219], v[70:73]
	v_mfma_f32_16x16x32_bf16 v[66:69], v[166:169], v[216:219], v[66:69]
	v_mfma_f32_16x16x32_bf16 v[126:129], v[170:173], v[188:191], v[126:129]
	v_mfma_f32_16x16x32_bf16 v[122:125], v[180:183], v[188:191], v[122:125]
	v_mfma_f32_16x16x32_bf16 v[110:113], v[170:173], v[196:199], v[110:113]
	v_mfma_f32_16x16x32_bf16 v[106:109], v[180:183], v[196:199], v[106:109]
	v_mfma_f32_16x16x32_bf16 v[94:97], v[170:173], v[204:207], v[94:97]
	v_mfma_f32_16x16x32_bf16 v[90:93], v[180:183], v[204:207], v[90:93]
	v_mfma_f32_16x16x32_bf16 v[78:81], v[170:173], v[212:215], v[78:81]
	v_mfma_f32_16x16x32_bf16 v[74:77], v[180:183], v[212:215], v[74:77]
	v_mfma_f32_16x16x32_bf16 v[126:129], v[174:177], v[192:195], v[126:129]
	v_mfma_f32_16x16x32_bf16 v[122:125], v[184:187], v[192:195], v[122:125]
	v_mfma_f32_16x16x32_bf16 v[110:113], v[174:177], v[200:203], v[110:113]
	v_mfma_f32_16x16x32_bf16 v[106:109], v[184:187], v[200:203], v[106:109]
	v_mfma_f32_16x16x32_bf16 v[94:97], v[174:177], v[208:211], v[94:97]
	v_mfma_f32_16x16x32_bf16 v[90:93], v[184:187], v[208:211], v[90:93]
	v_mfma_f32_16x16x32_bf16 v[78:81], v[174:177], v[216:219], v[78:81]
	v_mfma_f32_16x16x32_bf16 v[74:77], v[184:187], v[216:219], v[74:77]
	s_barrier
	s_setprio 0
	s_add_i32 s51, s42, s30
	v_lshl_add_u64 v[220:221], s[26:27], 0, v[134:135]
	s_mov_b32 m0, s51
	ds_read_b128 v[188:191], v157 offset:16384
	ds_read_b128 v[192:195], v157 offset:17408
	ds_read_b128 v[196:199], v157 offset:18432
	ds_read_b128 v[200:203], v157 offset:19456
	ds_read_b128 v[204:207], v157 offset:20480
	ds_read_b128 v[208:211], v157 offset:21504
	ds_read_b128 v[212:215], v157 offset:22528
	ds_read_b128 v[216:219], v157 offset:23552
	global_load_lds_dwordx4 v[220:221], off
	s_add_i32 m0, s51, 0x2000
	s_add_u32 s56, s26, 0x40000
	v_lshl_add_u64 v[222:223], s[26:27], 0, v[130:131]
	s_addc_u32 s57, s27, 0
	s_add_i32 s51, s43, s30
	global_load_lds_dwordx4 v[222:223], off
	v_lshl_add_u64 v[224:225], s[56:57], 0, v[134:135]
	s_mov_b32 m0, s51
	v_lshl_add_u64 v[226:227], s[28:29], 0, v[132:133]
	global_load_lds_dwordx4 v[224:225], off
	v_lshl_add_u64 v[224:225], s[56:57], 0, v[130:131]
	s_add_i32 m0, s51, 0x2000
	s_nop 0
	global_load_lds_dwordx4 v[224:225], off
	v_lshl_add_u64 v[224:225], s[28:29], 0, v[136:137]
	s_mov_b32 m0, s23
	s_nop 0
	global_load_lds_dwordx4 v[224:225], off
	s_mov_b32 m0, s34
	s_nop 0
	global_load_lds_dwordx4 v[226:227], off
	s_waitcnt vmcnt(8)
	s_waitcnt lgkmcnt(0)
	s_setprio 1
	s_barrier
	v_mfma_f32_16x16x32_bf16 v[54:57], v[148:151], v[188:191], v[54:57]
	v_mfma_f32_16x16x32_bf16 v[50:53], v[162:165], v[188:191], v[50:53]
	v_mfma_f32_16x16x32_bf16 v[38:41], v[148:151], v[196:199], v[38:41]
	v_mfma_f32_16x16x32_bf16 v[34:37], v[162:165], v[196:199], v[34:37]
	v_mfma_f32_16x16x32_bf16 v[22:25], v[148:151], v[204:207], v[22:25]
	v_mfma_f32_16x16x32_bf16 v[18:21], v[162:165], v[204:207], v[18:21]
	v_mfma_f32_16x16x32_bf16 v[6:9], v[148:151], v[212:215], v[6:9]
	v_mfma_f32_16x16x32_bf16 v[2:5], v[162:165], v[212:215], v[2:5]
	v_mfma_f32_16x16x32_bf16 v[54:57], v[158:161], v[192:195], v[54:57]
	v_mfma_f32_16x16x32_bf16 v[50:53], v[166:169], v[192:195], v[50:53]
	v_mfma_f32_16x16x32_bf16 v[38:41], v[158:161], v[200:203], v[38:41]
	v_mfma_f32_16x16x32_bf16 v[34:37], v[166:169], v[200:203], v[34:37]
	v_mfma_f32_16x16x32_bf16 v[22:25], v[158:161], v[208:211], v[22:25]
	v_mfma_f32_16x16x32_bf16 v[18:21], v[166:169], v[208:211], v[18:21]
	v_mfma_f32_16x16x32_bf16 v[6:9], v[158:161], v[216:219], v[6:9]
	v_mfma_f32_16x16x32_bf16 v[2:5], v[166:169], v[216:219], v[2:5]
	v_mfma_f32_16x16x32_bf16 v[62:65], v[170:173], v[188:191], v[62:65]
	v_mfma_f32_16x16x32_bf16 v[58:61], v[180:183], v[188:191], v[58:61]
	v_mfma_f32_16x16x32_bf16 v[46:49], v[170:173], v[196:199], v[46:49]
	v_mfma_f32_16x16x32_bf16 v[42:45], v[180:183], v[196:199], v[42:45]
	v_mfma_f32_16x16x32_bf16 v[30:33], v[170:173], v[204:207], v[30:33]
	v_mfma_f32_16x16x32_bf16 v[26:29], v[180:183], v[204:207], v[26:29]
	v_mfma_f32_16x16x32_bf16 v[14:17], v[170:173], v[212:215], v[14:17]
	v_mfma_f32_16x16x32_bf16 v[10:13], v[180:183], v[212:215], v[10:13]
	v_mfma_f32_16x16x32_bf16 v[62:65], v[174:177], v[192:195], v[62:65]
	v_mfma_f32_16x16x32_bf16 v[58:61], v[184:187], v[192:195], v[58:61]
	v_mfma_f32_16x16x32_bf16 v[46:49], v[174:177], v[200:203], v[46:49]
	v_mfma_f32_16x16x32_bf16 v[42:45], v[184:187], v[200:203], v[42:45]
	v_mfma_f32_16x16x32_bf16 v[30:33], v[174:177], v[208:211], v[30:33]
	v_mfma_f32_16x16x32_bf16 v[26:29], v[184:187], v[208:211], v[26:29]
	v_mfma_f32_16x16x32_bf16 v[14:17], v[174:177], v[216:219], v[14:17]
	v_mfma_f32_16x16x32_bf16 v[10:13], v[184:187], v[216:219], v[10:13]
	s_barrier
	s_setprio 0
	s_add_i32 s51, 0, 0x18000
	s_add_i32 s56, 0, 0x1c000
	v_add_u32_e32 v166, s51, v153
	v_add_u32_e32 v179, s56, v153
	ds_read_b128 v[148:151], v166
	ds_read_b128 v[158:161], v166 offset:1024
	ds_read_b128 v[162:165], v166 offset:2048
	ds_read_b128 v[166:169], v166 offset:3072
	ds_read_b128 v[170:173], v179
	ds_read_b128 v[174:177], v179 offset:1024
	ds_read_b128 v[180:183], v179 offset:2048
	ds_read_b128 v[184:187], v179 offset:3072
	s_add_u32 s28, s28, 0x40000
	s_addc_u32 s29, s29, 0
	s_mov_b32 m0, s35
	v_lshl_add_u64 v[228:229], s[28:29], 0, v[136:137]
	ds_read_b128 v[188:191], v157 offset:32768
	ds_read_b128 v[192:195], v157 offset:33792
	ds_read_b128 v[196:199], v157 offset:34816
	ds_read_b128 v[200:203], v157 offset:35840
	ds_read_b128 v[204:207], v157 offset:36864
	ds_read_b128 v[208:211], v157 offset:37888
	ds_read_b128 v[212:215], v157 offset:38912
	ds_read_b128 v[216:219], v157 offset:39936
	global_load_lds_dwordx4 v[228:229], off
	v_lshl_add_u64 v[228:229], s[28:29], 0, v[132:133]
	s_mov_b32 m0, s36
	s_nop 0
	global_load_lds_dwordx4 v[228:229], off
	s_waitcnt vmcnt(8)
	s_waitcnt lgkmcnt(0)
	s_setprio 1
	s_barrier
	v_mfma_f32_16x16x32_bf16 v[118:121], v[148:151], v[188:191], v[118:121]
	v_mfma_f32_16x16x32_bf16 v[114:117], v[162:165], v[188:191], v[114:117]
	v_mfma_f32_16x16x32_bf16 v[102:105], v[148:151], v[196:199], v[102:105]
	v_mfma_f32_16x16x32_bf16 v[98:101], v[162:165], v[196:199], v[98:101]
	v_mfma_f32_16x16x32_bf16 v[86:89], v[148:151], v[204:207], v[86:89]
	v_mfma_f32_16x16x32_bf16 v[82:85], v[162:165], v[204:207], v[82:85]
	v_mfma_f32_16x16x32_bf16 v[70:73], v[148:151], v[212:215], v[70:73]
	v_mfma_f32_16x16x32_bf16 v[66:69], v[162:165], v[212:215], v[66:69]
	v_mfma_f32_16x16x32_bf16 v[118:121], v[158:161], v[192:195], v[118:121]
	v_mfma_f32_16x16x32_bf16 v[114:117], v[166:169], v[192:195], v[114:117]
	v_mfma_f32_16x16x32_bf16 v[102:105], v[158:161], v[200:203], v[102:105]
	v_mfma_f32_16x16x32_bf16 v[98:101], v[166:169], v[200:203], v[98:101]
	v_mfma_f32_16x16x32_bf16 v[86:89], v[158:161], v[208:211], v[86:89]
	v_mfma_f32_16x16x32_bf16 v[82:85], v[166:169], v[208:211], v[82:85]
	v_mfma_f32_16x16x32_bf16 v[70:73], v[158:161], v[216:219], v[70:73]
	v_mfma_f32_16x16x32_bf16 v[66:69], v[166:169], v[216:219], v[66:69]
	v_mfma_f32_16x16x32_bf16 v[126:129], v[170:173], v[188:191], v[126:129]
	v_mfma_f32_16x16x32_bf16 v[122:125], v[180:183], v[188:191], v[122:125]
	v_mfma_f32_16x16x32_bf16 v[110:113], v[170:173], v[196:199], v[110:113]
	v_mfma_f32_16x16x32_bf16 v[106:109], v[180:183], v[196:199], v[106:109]
	v_mfma_f32_16x16x32_bf16 v[94:97], v[170:173], v[204:207], v[94:97]
	v_mfma_f32_16x16x32_bf16 v[90:93], v[180:183], v[204:207], v[90:93]
	v_mfma_f32_16x16x32_bf16 v[78:81], v[170:173], v[212:215], v[78:81]
	v_mfma_f32_16x16x32_bf16 v[74:77], v[180:183], v[212:215], v[74:77]
	v_mfma_f32_16x16x32_bf16 v[126:129], v[174:177], v[192:195], v[126:129]
	v_mfma_f32_16x16x32_bf16 v[122:125], v[184:187], v[192:195], v[122:125]
	v_mfma_f32_16x16x32_bf16 v[110:113], v[174:177], v[200:203], v[110:113]
	v_mfma_f32_16x16x32_bf16 v[106:109], v[184:187], v[200:203], v[106:109]
	v_mfma_f32_16x16x32_bf16 v[94:97], v[174:177], v[208:211], v[94:97]
	v_mfma_f32_16x16x32_bf16 v[90:93], v[184:187], v[208:211], v[90:93]
	v_mfma_f32_16x16x32_bf16 v[78:81], v[174:177], v[216:219], v[78:81]
	v_mfma_f32_16x16x32_bf16 v[74:77], v[184:187], v[216:219], v[74:77]
	s_barrier
	s_setprio 0
	s_add_i32 s28, s51, s30
	v_lshl_add_u64 v[220:221], v[220:221], 0, s[2:3]
	s_mov_b32 m0, s28
	ds_read_b128 v[188:191], v157 offset:49152
	ds_read_b128 v[192:195], v157 offset:50176
	ds_read_b128 v[196:199], v157 offset:51200
	ds_read_b128 v[200:203], v157 offset:52224
	ds_read_b128 v[204:207], v157 offset:53248
	ds_read_b128 v[208:211], v157 offset:54272
	ds_read_b128 v[212:215], v157 offset:55296
	ds_read_b128 v[216:219], v157 offset:56320
	global_load_lds_dwordx4 v[220:221], off
	s_add_i32 m0, s28, 0x2000
	s_add_u32 s26, s26, 0x40080
	v_lshl_add_u64 v[220:221], v[222:223], 0, s[2:3]
	s_addc_u32 s27, s27, 0
	s_add_i32 s28, s56, s30
	global_load_lds_dwordx4 v[220:221], off
	v_lshl_add_u64 v[220:221], s[26:27], 0, v[134:135]
	s_mov_b32 m0, s28
	s_nop 0
	global_load_lds_dwordx4 v[220:221], off
	v_lshl_add_u64 v[220:221], s[26:27], 0, v[130:131]
	s_add_i32 m0, s28, 0x2000
	s_nop 0
	global_load_lds_dwordx4 v[220:221], off
	v_lshl_add_u64 v[220:221], v[224:225], 0, s[2:3]
	s_mov_b32 m0, s38
	s_nop 0
	global_load_lds_dwordx4 v[220:221], off
	v_lshl_add_u64 v[220:221], v[226:227], 0, s[2:3]
	s_mov_b32 m0, s39
	s_nop 0
	global_load_lds_dwordx4 v[220:221], off
	s_waitcnt vmcnt(8)
	s_waitcnt lgkmcnt(0)
	s_setprio 1
	s_barrier
	v_mfma_f32_16x16x32_bf16 v[54:57], v[148:151], v[188:191], v[54:57]
	v_mfma_f32_16x16x32_bf16 v[50:53], v[162:165], v[188:191], v[50:53]
	v_mfma_f32_16x16x32_bf16 v[38:41], v[148:151], v[196:199], v[38:41]
	v_mfma_f32_16x16x32_bf16 v[34:37], v[162:165], v[196:199], v[34:37]
	v_mfma_f32_16x16x32_bf16 v[22:25], v[148:151], v[204:207], v[22:25]
	v_mfma_f32_16x16x32_bf16 v[18:21], v[162:165], v[204:207], v[18:21]
	v_mfma_f32_16x16x32_bf16 v[6:9], v[148:151], v[212:215], v[6:9]
	v_mfma_f32_16x16x32_bf16 v[2:5], v[162:165], v[212:215], v[2:5]
	v_mfma_f32_16x16x32_bf16 v[54:57], v[158:161], v[192:195], v[54:57]
	v_mfma_f32_16x16x32_bf16 v[50:53], v[166:169], v[192:195], v[50:53]
	v_mfma_f32_16x16x32_bf16 v[38:41], v[158:161], v[200:203], v[38:41]
	v_mfma_f32_16x16x32_bf16 v[34:37], v[166:169], v[200:203], v[34:37]
	v_mfma_f32_16x16x32_bf16 v[22:25], v[158:161], v[208:211], v[22:25]
	v_mfma_f32_16x16x32_bf16 v[18:21], v[166:169], v[208:211], v[18:21]
	v_mfma_f32_16x16x32_bf16 v[6:9], v[158:161], v[216:219], v[6:9]
	v_mfma_f32_16x16x32_bf16 v[2:5], v[166:169], v[216:219], v[2:5]
	v_mfma_f32_16x16x32_bf16 v[62:65], v[170:173], v[188:191], v[62:65]
	v_mfma_f32_16x16x32_bf16 v[58:61], v[180:183], v[188:191], v[58:61]
	v_mfma_f32_16x16x32_bf16 v[46:49], v[170:173], v[196:199], v[46:49]
	v_mfma_f32_16x16x32_bf16 v[42:45], v[180:183], v[196:199], v[42:45]
	v_mfma_f32_16x16x32_bf16 v[30:33], v[170:173], v[204:207], v[30:33]
	v_mfma_f32_16x16x32_bf16 v[26:29], v[180:183], v[204:207], v[26:29]
	v_mfma_f32_16x16x32_bf16 v[14:17], v[170:173], v[212:215], v[14:17]
	v_mfma_f32_16x16x32_bf16 v[10:13], v[180:183], v[212:215], v[10:13]
	v_mfma_f32_16x16x32_bf16 v[62:65], v[174:177], v[192:195], v[62:65]
	v_mfma_f32_16x16x32_bf16 v[58:61], v[184:187], v[192:195], v[58:61]
	v_mfma_f32_16x16x32_bf16 v[46:49], v[174:177], v[200:203], v[46:49]
	v_mfma_f32_16x16x32_bf16 v[42:45], v[184:187], v[200:203], v[42:45]
	v_mfma_f32_16x16x32_bf16 v[30:33], v[174:177], v[208:211], v[30:33]
	v_mfma_f32_16x16x32_bf16 v[26:29], v[184:187], v[208:211], v[26:29]
	v_mfma_f32_16x16x32_bf16 v[14:17], v[174:177], v[216:219], v[14:17]
	v_mfma_f32_16x16x32_bf16 v[10:13], v[184:187], v[216:219], v[10:13]
	s_barrier
	s_setprio 0
	s_add_i32 s50, s50, 2
	s_add_u32 s24, s24, 0x100
	s_addc_u32 s25, s25, 0
	s_add_u32 s48, s48, 0x100
	s_addc_u32 s49, s49, 0
	s_cmp_gt_u32 s50, 13
	s_cbranch_scc0 .LBB0_1054
	s_and_b64 vcc, exec, s[8:9]
	s_cbranch_vccz .LBB0_1057
	s_barrier

.LBB0_1124:
	ds_read_b128 v[86:89], v182
	ds_read_b128 v[90:93], v182 offset:1024
	ds_read_b128 v[98:101], v182 offset:2048
	ds_read_b128 v[102:105], v182 offset:3072
	ds_read_b128 v[164:167], v183
	ds_read_b128 v[168:171], v183 offset:1024
	ds_read_b128 v[172:175], v183 offset:2048
	ds_read_b128 v[186:189], v183 offset:3072
	s_add_u32 s34, s30, 0xfff80080
	s_addc_u32 s35, s31, -1
	s_cmp_eq_u32 s59, 28
	s_cselect_b32 s37, s21, s35
	s_cselect_b32 s36, s27, s34
	s_cselect_b32 s35, s19, s58
	s_cselect_b32 s34, s29, s57
	v_lshl_add_u64 v[176:177], s[30:31], 0, v[156:157]
	s_add_i32 m0, s38, 0xc000
	ds_read_b128 v[190:193], v184
	ds_read_b128 v[194:197], v184 offset:1024
	ds_read_b128 v[198:201], v184 offset:2048
	ds_read_b128 v[202:205], v184 offset:3072
	ds_read_b128 v[206:209], v184 offset:4096
	ds_read_b128 v[210:213], v184 offset:5120
	ds_read_b128 v[214:217], v184 offset:6144
	ds_read_b128 v[218:221], v184 offset:7168
	global_load_lds_dwordx4 v[176:177], off
	v_lshl_add_u64 v[176:177], s[30:31], 0, v[158:159]
	s_add_i32 m0, s38, 0xe000
	s_nop 0
	global_load_lds_dwordx4 v[176:177], off
	s_waitcnt vmcnt(8)
	s_waitcnt lgkmcnt(0)
	s_setprio 1
	s_barrier
	v_mfma_f32_16x16x32_bf16 v[142:145], v[86:89], v[190:193], v[142:145]
	v_mfma_f32_16x16x32_bf16 v[138:141], v[98:101], v[190:193], v[138:141]
	v_mfma_f32_16x16x32_bf16 v[126:129], v[86:89], v[198:201], v[126:129]
	v_mfma_f32_16x16x32_bf16 v[122:125], v[98:101], v[198:201], v[122:125]
	v_mfma_f32_16x16x32_bf16 v[110:113], v[86:89], v[206:209], v[110:113]
	v_mfma_f32_16x16x32_bf16 v[106:109], v[98:101], v[206:209], v[106:109]
	v_mfma_f32_16x16x32_bf16 v[78:81], v[86:89], v[214:217], v[78:81]
	v_mfma_f32_16x16x32_bf16 v[74:77], v[98:101], v[214:217], v[74:77]
	v_mfma_f32_16x16x32_bf16 v[142:145], v[90:93], v[194:197], v[142:145]
	v_mfma_f32_16x16x32_bf16 v[138:141], v[102:105], v[194:197], v[138:141]
	v_mfma_f32_16x16x32_bf16 v[126:129], v[90:93], v[202:205], v[126:129]
	v_mfma_f32_16x16x32_bf16 v[122:125], v[102:105], v[202:205], v[122:125]
	v_mfma_f32_16x16x32_bf16 v[110:113], v[90:93], v[210:213], v[110:113]
	v_mfma_f32_16x16x32_bf16 v[106:109], v[102:105], v[210:213], v[106:109]
	v_mfma_f32_16x16x32_bf16 v[78:81], v[90:93], v[218:221], v[78:81]
	v_mfma_f32_16x16x32_bf16 v[74:77], v[102:105], v[218:221], v[74:77]
	v_mfma_f32_16x16x32_bf16 v[134:137], v[164:167], v[190:193], v[134:137]
	v_mfma_f32_16x16x32_bf16 v[130:133], v[172:175], v[190:193], v[130:133]
	v_mfma_f32_16x16x32_bf16 v[118:121], v[164:167], v[198:201], v[118:121]
	v_mfma_f32_16x16x32_bf16 v[114:117], v[172:175], v[198:201], v[114:117]
	v_mfma_f32_16x16x32_bf16 v[94:97], v[164:167], v[206:209], v[94:97]
	v_mfma_f32_16x16x32_bf16 v[82:85], v[172:175], v[206:209], v[82:85]
	v_mfma_f32_16x16x32_bf16 v[70:73], v[164:167], v[214:217], v[70:73]
	v_mfma_f32_16x16x32_bf16 v[66:69], v[172:175], v[214:217], v[66:69]
	v_mfma_f32_16x16x32_bf16 v[134:137], v[168:171], v[194:197], v[134:137]
	v_mfma_f32_16x16x32_bf16 v[130:133], v[186:189], v[194:197], v[130:133]
	v_mfma_f32_16x16x32_bf16 v[118:121], v[168:171], v[202:205], v[118:121]
	v_mfma_f32_16x16x32_bf16 v[114:117], v[186:189], v[202:205], v[114:117]
	v_mfma_f32_16x16x32_bf16 v[94:97], v[168:171], v[210:213], v[94:97]
	v_mfma_f32_16x16x32_bf16 v[82:85], v[186:189], v[210:213], v[82:85]
	v_mfma_f32_16x16x32_bf16 v[70:73], v[168:171], v[218:221], v[70:73]
	v_mfma_f32_16x16x32_bf16 v[66:69], v[186:189], v[218:221], v[66:69]
	s_barrier
	s_setprio 0
	s_add_i32 s68, s51, s33
	v_lshl_add_u64 v[176:177], s[34:35], 0, v[150:151]
	s_mov_b32 m0, s68
	ds_read_b128 v[190:193], v184 offset:16384
	ds_read_b128 v[194:197], v184 offset:17408
	ds_read_b128 v[198:201], v184 offset:18432
	ds_read_b128 v[202:205], v184 offset:19456
	ds_read_b128 v[206:209], v184 offset:20480
	ds_read_b128 v[210:213], v184 offset:21504
	ds_read_b128 v[214:217], v184 offset:22528
	ds_read_b128 v[218:221], v184 offset:23552
	global_load_lds_dwordx4 v[176:177], off
	s_add_i32 m0, s68, 0x2000
	s_add_u32 s68, s34, 0x80000
	v_lshl_add_u64 v[222:223], s[34:35], 0, v[154:155]
	s_addc_u32 s69, s35, 0
	s_add_i32 s70, s56, s33
	global_load_lds_dwordx4 v[222:223], off
	v_lshl_add_u64 v[224:225], s[68:69], 0, v[150:151]
	s_mov_b32 m0, s70
	v_lshl_add_u64 v[226:227], s[36:37], 0, v[152:153]
	global_load_lds_dwordx4 v[224:225], off
	v_lshl_add_u64 v[224:225], s[68:69], 0, v[154:155]
	s_add_i32 m0, s70, 0x2000
	s_nop 0
	global_load_lds_dwordx4 v[224:225], off
	v_lshl_add_u64 v[224:225], s[36:37], 0, v[148:149]
	s_mov_b32 m0, s38
	s_nop 0
	global_load_lds_dwordx4 v[224:225], off
	s_mov_b32 m0, s39
	s_nop 0
	global_load_lds_dwordx4 v[226:227], off
	s_waitcnt vmcnt(8)
	s_waitcnt lgkmcnt(0)
	s_setprio 1
	s_barrier
	v_mfma_f32_16x16x32_bf16 v[62:65], v[86:89], v[190:193], v[62:65]
	v_mfma_f32_16x16x32_bf16 v[58:61], v[98:101], v[190:193], v[58:61]
	v_mfma_f32_16x16x32_bf16 v[46:49], v[86:89], v[198:201], v[46:49]
	v_mfma_f32_16x16x32_bf16 v[42:45], v[98:101], v[198:201], v[42:45]
	v_mfma_f32_16x16x32_bf16 v[30:33], v[86:89], v[206:209], v[30:33]
	v_mfma_f32_16x16x32_bf16 v[26:29], v[98:101], v[206:209], v[26:29]
	v_mfma_f32_16x16x32_bf16 v[14:17], v[86:89], v[214:217], v[14:17]
	v_mfma_f32_16x16x32_bf16 v[10:13], v[98:101], v[214:217], v[10:13]
	v_mfma_f32_16x16x32_bf16 v[62:65], v[90:93], v[194:197], v[62:65]
	v_mfma_f32_16x16x32_bf16 v[58:61], v[102:105], v[194:197], v[58:61]
	v_mfma_f32_16x16x32_bf16 v[46:49], v[90:93], v[202:205], v[46:49]
	v_mfma_f32_16x16x32_bf16 v[42:45], v[102:105], v[202:205], v[42:45]
	v_mfma_f32_16x16x32_bf16 v[30:33], v[90:93], v[210:213], v[30:33]
	v_mfma_f32_16x16x32_bf16 v[26:29], v[102:105], v[210:213], v[26:29]
	v_mfma_f32_16x16x32_bf16 v[14:17], v[90:93], v[218:221], v[14:17]
	v_mfma_f32_16x16x32_bf16 v[10:13], v[102:105], v[218:221], v[10:13]
	v_mfma_f32_16x16x32_bf16 v[54:57], v[164:167], v[190:193], v[54:57]
	v_mfma_f32_16x16x32_bf16 v[50:53], v[172:175], v[190:193], v[50:53]
	v_mfma_f32_16x16x32_bf16 v[38:41], v[164:167], v[198:201], v[38:41]
	v_mfma_f32_16x16x32_bf16 v[34:37], v[172:175], v[198:201], v[34:37]
	v_mfma_f32_16x16x32_bf16 v[22:25], v[164:167], v[206:209], v[22:25]
	v_mfma_f32_16x16x32_bf16 v[18:21], v[172:175], v[206:209], v[18:21]
	v_mfma_f32_16x16x32_bf16 v[6:9], v[164:167], v[214:217], v[6:9]
	v_mfma_f32_16x16x32_bf16 v[2:5], v[172:175], v[214:217], v[2:5]
	v_mfma_f32_16x16x32_bf16 v[54:57], v[168:171], v[194:197], v[54:57]
	v_mfma_f32_16x16x32_bf16 v[50:53], v[186:189], v[194:197], v[50:53]
	v_mfma_f32_16x16x32_bf16 v[38:41], v[168:171], v[202:205], v[38:41]
	v_mfma_f32_16x16x32_bf16 v[34:37], v[186:189], v[202:205], v[34:37]
	v_mfma_f32_16x16x32_bf16 v[22:25], v[168:171], v[210:213], v[22:25]
	v_mfma_f32_16x16x32_bf16 v[18:21], v[186:189], v[210:213], v[18:21]
	v_mfma_f32_16x16x32_bf16 v[6:9], v[168:171], v[218:221], v[6:9]
	v_mfma_f32_16x16x32_bf16 v[2:5], v[186:189], v[218:221], v[2:5]
	s_barrier
	s_setprio 0
	s_add_i32 s68, 0, 0x18000
	s_add_i32 s69, 0, 0x1c000
	v_add_u32_e32 v102, s68, v180
	v_add_u32_e32 v185, s69, v180
	ds_read_b128 v[86:89], v102
	ds_read_b128 v[90:93], v102 offset:1024
	ds_read_b128 v[98:101], v102 offset:2048
	ds_read_b128 v[102:105], v102 offset:3072
	ds_read_b128 v[164:167], v185
	ds_read_b128 v[168:171], v185 offset:1024
	ds_read_b128 v[172:175], v185 offset:2048
	ds_read_b128 v[186:189], v185 offset:3072
	s_add_u32 s36, s36, 0x80000
	s_addc_u32 s37, s37, 0
	s_mov_b32 m0, s40
	v_lshl_add_u64 v[228:229], s[36:37], 0, v[148:149]
	ds_read_b128 v[190:193], v184 offset:32768
	ds_read_b128 v[194:197], v184 offset:33792
	ds_read_b128 v[198:201], v184 offset:34816
	ds_read_b128 v[202:205], v184 offset:35840
	ds_read_b128 v[206:209], v184 offset:36864
	ds_read_b128 v[210:213], v184 offset:37888
	ds_read_b128 v[214:217], v184 offset:38912
	ds_read_b128 v[218:221], v184 offset:39936
	global_load_lds_dwordx4 v[228:229], off
	v_lshl_add_u64 v[228:229], s[36:37], 0, v[152:153]
	s_mov_b32 m0, s41
	s_nop 0
	global_load_lds_dwordx4 v[228:229], off
	s_waitcnt vmcnt(8)
	s_waitcnt lgkmcnt(0)
	s_setprio 1
	s_barrier
	v_mfma_f32_16x16x32_bf16 v[142:145], v[86:89], v[190:193], v[142:145]
	v_mfma_f32_16x16x32_bf16 v[138:141], v[98:101], v[190:193], v[138:141]
	v_mfma_f32_16x16x32_bf16 v[126:129], v[86:89], v[198:201], v[126:129]
	v_mfma_f32_16x16x32_bf16 v[122:125], v[98:101], v[198:201], v[122:125]
	v_mfma_f32_16x16x32_bf16 v[110:113], v[86:89], v[206:209], v[110:113]
	v_mfma_f32_16x16x32_bf16 v[106:109], v[98:101], v[206:209], v[106:109]
	v_mfma_f32_16x16x32_bf16 v[78:81], v[86:89], v[214:217], v[78:81]
	v_mfma_f32_16x16x32_bf16 v[74:77], v[98:101], v[214:217], v[74:77]
	v_mfma_f32_16x16x32_bf16 v[142:145], v[90:93], v[194:197], v[142:145]
	v_mfma_f32_16x16x32_bf16 v[138:141], v[102:105], v[194:197], v[138:141]
	v_mfma_f32_16x16x32_bf16 v[126:129], v[90:93], v[202:205], v[126:129]
	v_mfma_f32_16x16x32_bf16 v[122:125], v[102:105], v[202:205], v[122:125]
	v_mfma_f32_16x16x32_bf16 v[110:113], v[90:93], v[210:213], v[110:113]
	v_mfma_f32_16x16x32_bf16 v[106:109], v[102:105], v[210:213], v[106:109]
	v_mfma_f32_16x16x32_bf16 v[78:81], v[90:93], v[218:221], v[78:81]
	v_mfma_f32_16x16x32_bf16 v[74:77], v[102:105], v[218:221], v[74:77]
	v_mfma_f32_16x16x32_bf16 v[134:137], v[164:167], v[190:193], v[134:137]
	v_mfma_f32_16x16x32_bf16 v[130:133], v[172:175], v[190:193], v[130:133]
	v_mfma_f32_16x16x32_bf16 v[118:121], v[164:167], v[198:201], v[118:121]
	v_mfma_f32_16x16x32_bf16 v[114:117], v[172:175], v[198:201], v[114:117]
	v_mfma_f32_16x16x32_bf16 v[94:97], v[164:167], v[206:209], v[94:97]
	v_mfma_f32_16x16x32_bf16 v[82:85], v[172:175], v[206:209], v[82:85]
	v_mfma_f32_16x16x32_bf16 v[70:73], v[164:167], v[214:217], v[70:73]
	v_mfma_f32_16x16x32_bf16 v[66:69], v[172:175], v[214:217], v[66:69]
	v_mfma_f32_16x16x32_bf16 v[134:137], v[168:171], v[194:197], v[134:137]
	v_mfma_f32_16x16x32_bf16 v[130:133], v[186:189], v[194:197], v[130:133]
	v_mfma_f32_16x16x32_bf16 v[118:121], v[168:171], v[202:205], v[118:121]
	v_mfma_f32_16x16x32_bf16 v[114:117], v[186:189], v[202:205], v[114:117]
	v_mfma_f32_16x16x32_bf16 v[94:97], v[168:171], v[210:213], v[94:97]
	v_mfma_f32_16x16x32_bf16 v[82:85], v[186:189], v[210:213], v[82:85]
	v_mfma_f32_16x16x32_bf16 v[70:73], v[168:171], v[218:221], v[70:73]
	v_mfma_f32_16x16x32_bf16 v[66:69], v[186:189], v[218:221], v[66:69]
	s_barrier
	s_setprio 0
	s_add_i32 s36, s68, s33
	v_lshl_add_u64 v[176:177], v[176:177], 0, s[2:3]
	s_mov_b32 m0, s36
	ds_read_b128 v[190:193], v184 offset:49152
	ds_read_b128 v[194:197], v184 offset:50176
	ds_read_b128 v[198:201], v184 offset:51200
	ds_read_b128 v[202:205], v184 offset:52224
	ds_read_b128 v[206:209], v184 offset:53248
	ds_read_b128 v[210:213], v184 offset:54272
	ds_read_b128 v[214:217], v184 offset:55296
	ds_read_b128 v[218:221], v184 offset:56320
	global_load_lds_dwordx4 v[176:177], off
	s_add_i32 m0, s36, 0x2000
	s_add_u32 s34, s34, 0x80080
	v_lshl_add_u64 v[176:177], v[222:223], 0, s[2:3]
	s_addc_u32 s35, s35, 0
	s_add_i32 s36, s69, s33
	global_load_lds_dwordx4 v[176:177], off
	v_lshl_add_u64 v[176:177], s[34:35], 0, v[150:151]
	s_mov_b32 m0, s36
	s_nop 0
	global_load_lds_dwordx4 v[176:177], off
	v_lshl_add_u64 v[176:177], s[34:35], 0, v[154:155]
	s_add_i32 m0, s36, 0x2000
	s_nop 0
	global_load_lds_dwordx4 v[176:177], off
	v_lshl_add_u64 v[176:177], v[224:225], 0, s[2:3]
	s_mov_b32 m0, s43
	s_nop 0
	global_load_lds_dwordx4 v[176:177], off
	v_lshl_add_u64 v[176:177], v[226:227], 0, s[2:3]
	s_mov_b32 m0, s44
	s_nop 0
	global_load_lds_dwordx4 v[176:177], off
	s_waitcnt vmcnt(8)
	s_waitcnt lgkmcnt(0)
	s_setprio 1
	s_barrier
	v_mfma_f32_16x16x32_bf16 v[62:65], v[86:89], v[190:193], v[62:65]
	v_mfma_f32_16x16x32_bf16 v[58:61], v[98:101], v[190:193], v[58:61]
	v_mfma_f32_16x16x32_bf16 v[46:49], v[86:89], v[198:201], v[46:49]
	v_mfma_f32_16x16x32_bf16 v[42:45], v[98:101], v[198:201], v[42:45]
	v_mfma_f32_16x16x32_bf16 v[30:33], v[86:89], v[206:209], v[30:33]
	v_mfma_f32_16x16x32_bf16 v[26:29], v[98:101], v[206:209], v[26:29]
	v_mfma_f32_16x16x32_bf16 v[14:17], v[86:89], v[214:217], v[14:17]
	v_mfma_f32_16x16x32_bf16 v[10:13], v[98:101], v[214:217], v[10:13]
	v_mfma_f32_16x16x32_bf16 v[62:65], v[90:93], v[194:197], v[62:65]
	v_mfma_f32_16x16x32_bf16 v[58:61], v[102:105], v[194:197], v[58:61]
	v_mfma_f32_16x16x32_bf16 v[46:49], v[90:93], v[202:205], v[46:49]
	v_mfma_f32_16x16x32_bf16 v[42:45], v[102:105], v[202:205], v[42:45]
	v_mfma_f32_16x16x32_bf16 v[30:33], v[90:93], v[210:213], v[30:33]
	v_mfma_f32_16x16x32_bf16 v[26:29], v[102:105], v[210:213], v[26:29]
	v_mfma_f32_16x16x32_bf16 v[14:17], v[90:93], v[218:221], v[14:17]
	v_mfma_f32_16x16x32_bf16 v[10:13], v[102:105], v[218:221], v[10:13]
	v_mfma_f32_16x16x32_bf16 v[54:57], v[164:167], v[190:193], v[54:57]
	v_mfma_f32_16x16x32_bf16 v[50:53], v[172:175], v[190:193], v[50:53]
	v_mfma_f32_16x16x32_bf16 v[38:41], v[164:167], v[198:201], v[38:41]
	v_mfma_f32_16x16x32_bf16 v[34:37], v[172:175], v[198:201], v[34:37]
	v_mfma_f32_16x16x32_bf16 v[22:25], v[164:167], v[206:209], v[22:25]
	v_mfma_f32_16x16x32_bf16 v[18:21], v[172:175], v[206:209], v[18:21]
	v_mfma_f32_16x16x32_bf16 v[6:9], v[164:167], v[214:217], v[6:9]
	v_mfma_f32_16x16x32_bf16 v[2:5], v[172:175], v[214:217], v[2:5]
	v_mfma_f32_16x16x32_bf16 v[54:57], v[168:171], v[194:197], v[54:57]
	v_mfma_f32_16x16x32_bf16 v[50:53], v[186:189], v[194:197], v[50:53]
	v_mfma_f32_16x16x32_bf16 v[38:41], v[168:171], v[202:205], v[38:41]
	v_mfma_f32_16x16x32_bf16 v[34:37], v[186:189], v[202:205], v[34:37]
	v_mfma_f32_16x16x32_bf16 v[22:25], v[168:171], v[210:213], v[22:25]
	v_mfma_f32_16x16x32_bf16 v[18:21], v[186:189], v[210:213], v[18:21]
	v_mfma_f32_16x16x32_bf16 v[6:9], v[168:171], v[218:221], v[6:9]
	v_mfma_f32_16x16x32_bf16 v[2:5], v[186:189], v[218:221], v[2:5]
	s_barrier
	s_setprio 0
	s_add_i32 s59, s59, 2
	s_add_u32 s30, s30, 0x100
	s_addc_u32 s31, s31, 0
	s_add_u32 s57, s57, 0x100
	s_addc_u32 s58, s58, 0
	s_cmp_gt_u32 s59, 29
	s_cbranch_scc0 .LBB0_1124
	s_and_b64 vcc, exec, s[16:17]
	s_cbranch_vccz .LBB0_1127
	s_barrier

.LBB0_1208:
	ds_read_b128 v[98:101], v175
	ds_read_b128 v[102:105], v175 offset:1024
	ds_read_b128 v[106:109], v175 offset:2048
	ds_read_b128 v[110:113], v175 offset:3072
	ds_read_b128 v[164:167], v176
	ds_read_b128 v[168:171], v176 offset:1024
	ds_read_b128 v[182:185], v176 offset:2048
	ds_read_b128 v[186:189], v176 offset:3072
	s_add_u32 s28, s26, 0xfff80080
	s_addc_u32 s29, s27, -1
	s_cmp_eq_u32 s58, 28
	s_cselect_b32 s31, s21, s29
	s_cselect_b32 s30, s50, s28
	s_cselect_b32 s29, s19, s57
	s_cselect_b32 s28, s51, s56
	v_lshl_add_u64 v[222:223], s[26:27], 0, v[156:157]
	s_add_i32 m0, s36, 0xc000
	ds_read_b128 v[190:193], v177
	ds_read_b128 v[194:197], v177 offset:1024
	ds_read_b128 v[198:201], v177 offset:2048
	ds_read_b128 v[202:205], v177 offset:3072
	ds_read_b128 v[206:209], v177 offset:4096
	ds_read_b128 v[210:213], v177 offset:5120
	ds_read_b128 v[214:217], v177 offset:6144
	ds_read_b128 v[218:221], v177 offset:7168
	global_load_lds_dwordx4 v[222:223], off
	v_lshl_add_u64 v[222:223], s[26:27], 0, v[158:159]
	s_add_i32 m0, s36, 0xe000
	s_nop 0
	global_load_lds_dwordx4 v[222:223], off
	s_waitcnt vmcnt(8)
	s_waitcnt lgkmcnt(0)
	s_setprio 1
	s_barrier
	v_mfma_f32_16x16x32_bf16 v[142:145], v[98:101], v[190:193], v[142:145]
	v_mfma_f32_16x16x32_bf16 v[138:141], v[106:109], v[190:193], v[138:141]
	v_mfma_f32_16x16x32_bf16 v[126:129], v[98:101], v[198:201], v[126:129]
	v_mfma_f32_16x16x32_bf16 v[122:125], v[106:109], v[198:201], v[122:125]
	v_mfma_f32_16x16x32_bf16 v[94:97], v[98:101], v[206:209], v[94:97]
	v_mfma_f32_16x16x32_bf16 v[90:93], v[106:109], v[206:209], v[90:93]
	v_mfma_f32_16x16x32_bf16 v[78:81], v[98:101], v[214:217], v[78:81]
	v_mfma_f32_16x16x32_bf16 v[74:77], v[106:109], v[214:217], v[74:77]
	v_mfma_f32_16x16x32_bf16 v[142:145], v[102:105], v[194:197], v[142:145]
	v_mfma_f32_16x16x32_bf16 v[138:141], v[110:113], v[194:197], v[138:141]
	v_mfma_f32_16x16x32_bf16 v[126:129], v[102:105], v[202:205], v[126:129]
	v_mfma_f32_16x16x32_bf16 v[122:125], v[110:113], v[202:205], v[122:125]
	v_mfma_f32_16x16x32_bf16 v[94:97], v[102:105], v[210:213], v[94:97]
	v_mfma_f32_16x16x32_bf16 v[90:93], v[110:113], v[210:213], v[90:93]
	v_mfma_f32_16x16x32_bf16 v[78:81], v[102:105], v[218:221], v[78:81]
	v_mfma_f32_16x16x32_bf16 v[74:77], v[110:113], v[218:221], v[74:77]
	v_mfma_f32_16x16x32_bf16 v[134:137], v[164:167], v[190:193], v[134:137]
	v_mfma_f32_16x16x32_bf16 v[130:133], v[182:185], v[190:193], v[130:133]
	v_mfma_f32_16x16x32_bf16 v[118:121], v[164:167], v[198:201], v[118:121]
	v_mfma_f32_16x16x32_bf16 v[114:117], v[182:185], v[198:201], v[114:117]
	v_mfma_f32_16x16x32_bf16 v[86:89], v[164:167], v[206:209], v[86:89]
	v_mfma_f32_16x16x32_bf16 v[82:85], v[182:185], v[206:209], v[82:85]
	v_mfma_f32_16x16x32_bf16 v[70:73], v[164:167], v[214:217], v[70:73]
	v_mfma_f32_16x16x32_bf16 v[66:69], v[182:185], v[214:217], v[66:69]
	v_mfma_f32_16x16x32_bf16 v[134:137], v[168:171], v[194:197], v[134:137]
	v_mfma_f32_16x16x32_bf16 v[130:133], v[186:189], v[194:197], v[130:133]
	v_mfma_f32_16x16x32_bf16 v[118:121], v[168:171], v[202:205], v[118:121]
	v_mfma_f32_16x16x32_bf16 v[114:117], v[186:189], v[202:205], v[114:117]
	v_mfma_f32_16x16x32_bf16 v[86:89], v[168:171], v[210:213], v[86:89]
	v_mfma_f32_16x16x32_bf16 v[82:85], v[186:189], v[210:213], v[82:85]
	v_mfma_f32_16x16x32_bf16 v[70:73], v[168:171], v[218:221], v[70:73]
	v_mfma_f32_16x16x32_bf16 v[66:69], v[186:189], v[218:221], v[66:69]
	s_barrier
	s_setprio 0
	s_add_i32 s59, s45, s33
	v_lshl_add_u64 v[222:223], s[28:29], 0, v[152:153]
	s_mov_b32 m0, s59
	ds_read_b128 v[190:193], v177 offset:16384
	ds_read_b128 v[194:197], v177 offset:17408
	ds_read_b128 v[198:201], v177 offset:18432
	ds_read_b128 v[202:205], v177 offset:19456
	ds_read_b128 v[206:209], v177 offset:20480
	ds_read_b128 v[210:213], v177 offset:21504
	ds_read_b128 v[214:217], v177 offset:22528
	ds_read_b128 v[218:221], v177 offset:23552
	global_load_lds_dwordx4 v[222:223], off
	s_add_i32 m0, s59, 0x2000
	s_add_u32 s68, s28, 0x80000
	v_lshl_add_u64 v[224:225], s[28:29], 0, v[148:149]
	s_addc_u32 s69, s29, 0
	s_add_i32 s59, s46, s33
	global_load_lds_dwordx4 v[224:225], off
	v_lshl_add_u64 v[226:227], s[68:69], 0, v[152:153]
	s_mov_b32 m0, s59
	v_lshl_add_u64 v[228:229], s[30:31], 0, v[150:151]
	global_load_lds_dwordx4 v[226:227], off
	v_lshl_add_u64 v[226:227], s[68:69], 0, v[148:149]
	s_add_i32 m0, s59, 0x2000
	s_nop 0
	global_load_lds_dwordx4 v[226:227], off
	v_lshl_add_u64 v[226:227], s[30:31], 0, v[154:155]
	s_mov_b32 m0, s36
	s_nop 0
	global_load_lds_dwordx4 v[226:227], off
	s_mov_b32 m0, s37
	s_nop 0
	global_load_lds_dwordx4 v[228:229], off
	s_waitcnt vmcnt(8)
	s_waitcnt lgkmcnt(0)
	s_setprio 1
	s_barrier
	v_mfma_f32_16x16x32_bf16 v[62:65], v[98:101], v[190:193], v[62:65]
	v_mfma_f32_16x16x32_bf16 v[58:61], v[106:109], v[190:193], v[58:61]
	v_mfma_f32_16x16x32_bf16 v[46:49], v[98:101], v[198:201], v[46:49]
	v_mfma_f32_16x16x32_bf16 v[42:45], v[106:109], v[198:201], v[42:45]
	v_mfma_f32_16x16x32_bf16 v[30:33], v[98:101], v[206:209], v[30:33]
	v_mfma_f32_16x16x32_bf16 v[26:29], v[106:109], v[206:209], v[26:29]
	v_mfma_f32_16x16x32_bf16 v[14:17], v[98:101], v[214:217], v[14:17]
	v_mfma_f32_16x16x32_bf16 v[10:13], v[106:109], v[214:217], v[10:13]
	v_mfma_f32_16x16x32_bf16 v[62:65], v[102:105], v[194:197], v[62:65]
	v_mfma_f32_16x16x32_bf16 v[58:61], v[110:113], v[194:197], v[58:61]
	v_mfma_f32_16x16x32_bf16 v[46:49], v[102:105], v[202:205], v[46:49]
	v_mfma_f32_16x16x32_bf16 v[42:45], v[110:113], v[202:205], v[42:45]
	v_mfma_f32_16x16x32_bf16 v[30:33], v[102:105], v[210:213], v[30:33]
	v_mfma_f32_16x16x32_bf16 v[26:29], v[110:113], v[210:213], v[26:29]
	v_mfma_f32_16x16x32_bf16 v[14:17], v[102:105], v[218:221], v[14:17]
	v_mfma_f32_16x16x32_bf16 v[10:13], v[110:113], v[218:221], v[10:13]
	v_mfma_f32_16x16x32_bf16 v[54:57], v[164:167], v[190:193], v[54:57]
	v_mfma_f32_16x16x32_bf16 v[50:53], v[182:185], v[190:193], v[50:53]
	v_mfma_f32_16x16x32_bf16 v[38:41], v[164:167], v[198:201], v[38:41]
	v_mfma_f32_16x16x32_bf16 v[34:37], v[182:185], v[198:201], v[34:37]
	v_mfma_f32_16x16x32_bf16 v[22:25], v[164:167], v[206:209], v[22:25]
	v_mfma_f32_16x16x32_bf16 v[18:21], v[182:185], v[206:209], v[18:21]
	v_mfma_f32_16x16x32_bf16 v[6:9], v[164:167], v[214:217], v[6:9]
	v_mfma_f32_16x16x32_bf16 v[2:5], v[182:185], v[214:217], v[2:5]
	v_mfma_f32_16x16x32_bf16 v[54:57], v[168:171], v[194:197], v[54:57]
	v_mfma_f32_16x16x32_bf16 v[50:53], v[186:189], v[194:197], v[50:53]
	v_mfma_f32_16x16x32_bf16 v[38:41], v[168:171], v[202:205], v[38:41]
	v_mfma_f32_16x16x32_bf16 v[34:37], v[186:189], v[202:205], v[34:37]
	v_mfma_f32_16x16x32_bf16 v[22:25], v[168:171], v[210:213], v[22:25]
	v_mfma_f32_16x16x32_bf16 v[18:21], v[186:189], v[210:213], v[18:21]
	v_mfma_f32_16x16x32_bf16 v[6:9], v[168:171], v[218:221], v[6:9]
	v_mfma_f32_16x16x32_bf16 v[2:5], v[186:189], v[218:221], v[2:5]
	s_barrier
	s_setprio 0
	s_add_i32 s59, 0, 0x18000
	s_add_i32 s68, 0, 0x1c000
	v_add_u32_e32 v110, s59, v173
	v_add_u32_e32 v181, s68, v173
	ds_read_b128 v[98:101], v110
	ds_read_b128 v[102:105], v110 offset:1024
	ds_read_b128 v[106:109], v110 offset:2048
	ds_read_b128 v[110:113], v110 offset:3072
	ds_read_b128 v[164:167], v181
	ds_read_b128 v[168:171], v181 offset:1024
	ds_read_b128 v[182:185], v181 offset:2048
	ds_read_b128 v[186:189], v181 offset:3072
	s_add_u32 s30, s30, 0x80000
	s_addc_u32 s31, s31, 0
	s_mov_b32 m0, s38
	v_lshl_add_u64 v[230:231], s[30:31], 0, v[154:155]
	ds_read_b128 v[190:193], v177 offset:32768
	ds_read_b128 v[194:197], v177 offset:33792
	ds_read_b128 v[198:201], v177 offset:34816
	ds_read_b128 v[202:205], v177 offset:35840
	ds_read_b128 v[206:209], v177 offset:36864
	ds_read_b128 v[210:213], v177 offset:37888
	ds_read_b128 v[214:217], v177 offset:38912
	ds_read_b128 v[218:221], v177 offset:39936
	global_load_lds_dwordx4 v[230:231], off
	v_lshl_add_u64 v[230:231], s[30:31], 0, v[150:151]
	s_mov_b32 m0, s39
	s_nop 0
	global_load_lds_dwordx4 v[230:231], off
	s_waitcnt vmcnt(8)
	s_waitcnt lgkmcnt(0)
	s_setprio 1
	s_barrier
	v_mfma_f32_16x16x32_bf16 v[142:145], v[98:101], v[190:193], v[142:145]
	v_mfma_f32_16x16x32_bf16 v[138:141], v[106:109], v[190:193], v[138:141]
	v_mfma_f32_16x16x32_bf16 v[126:129], v[98:101], v[198:201], v[126:129]
	v_mfma_f32_16x16x32_bf16 v[122:125], v[106:109], v[198:201], v[122:125]
	v_mfma_f32_16x16x32_bf16 v[94:97], v[98:101], v[206:209], v[94:97]
	v_mfma_f32_16x16x32_bf16 v[90:93], v[106:109], v[206:209], v[90:93]
	v_mfma_f32_16x16x32_bf16 v[78:81], v[98:101], v[214:217], v[78:81]
	v_mfma_f32_16x16x32_bf16 v[74:77], v[106:109], v[214:217], v[74:77]
	v_mfma_f32_16x16x32_bf16 v[142:145], v[102:105], v[194:197], v[142:145]
	v_mfma_f32_16x16x32_bf16 v[138:141], v[110:113], v[194:197], v[138:141]
	v_mfma_f32_16x16x32_bf16 v[126:129], v[102:105], v[202:205], v[126:129]
	v_mfma_f32_16x16x32_bf16 v[122:125], v[110:113], v[202:205], v[122:125]
	v_mfma_f32_16x16x32_bf16 v[94:97], v[102:105], v[210:213], v[94:97]
	v_mfma_f32_16x16x32_bf16 v[90:93], v[110:113], v[210:213], v[90:93]
	v_mfma_f32_16x16x32_bf16 v[78:81], v[102:105], v[218:221], v[78:81]
	v_mfma_f32_16x16x32_bf16 v[74:77], v[110:113], v[218:221], v[74:77]
	v_mfma_f32_16x16x32_bf16 v[134:137], v[164:167], v[190:193], v[134:137]
	v_mfma_f32_16x16x32_bf16 v[130:133], v[182:185], v[190:193], v[130:133]
	v_mfma_f32_16x16x32_bf16 v[118:121], v[164:167], v[198:201], v[118:121]
	v_mfma_f32_16x16x32_bf16 v[114:117], v[182:185], v[198:201], v[114:117]
	v_mfma_f32_16x16x32_bf16 v[86:89], v[164:167], v[206:209], v[86:89]
	v_mfma_f32_16x16x32_bf16 v[82:85], v[182:185], v[206:209], v[82:85]
	v_mfma_f32_16x16x32_bf16 v[70:73], v[164:167], v[214:217], v[70:73]
	v_mfma_f32_16x16x32_bf16 v[66:69], v[182:185], v[214:217], v[66:69]
	v_mfma_f32_16x16x32_bf16 v[134:137], v[168:171], v[194:197], v[134:137]
	v_mfma_f32_16x16x32_bf16 v[130:133], v[186:189], v[194:197], v[130:133]
	v_mfma_f32_16x16x32_bf16 v[118:121], v[168:171], v[202:205], v[118:121]
	v_mfma_f32_16x16x32_bf16 v[114:117], v[186:189], v[202:205], v[114:117]
	v_mfma_f32_16x16x32_bf16 v[86:89], v[168:171], v[210:213], v[86:89]
	v_mfma_f32_16x16x32_bf16 v[82:85], v[186:189], v[210:213], v[82:85]
	v_mfma_f32_16x16x32_bf16 v[70:73], v[168:171], v[218:221], v[70:73]
	v_mfma_f32_16x16x32_bf16 v[66:69], v[186:189], v[218:221], v[66:69]
	s_barrier
	s_setprio 0
	s_add_i32 s30, s59, s33
	v_lshl_add_u64 v[222:223], v[222:223], 0, s[8:9]
	s_mov_b32 m0, s30
	ds_read_b128 v[190:193], v177 offset:49152
	ds_read_b128 v[194:197], v177 offset:50176
	ds_read_b128 v[198:201], v177 offset:51200
	ds_read_b128 v[202:205], v177 offset:52224
	ds_read_b128 v[206:209], v177 offset:53248
	ds_read_b128 v[210:213], v177 offset:54272
	ds_read_b128 v[214:217], v177 offset:55296
	ds_read_b128 v[218:221], v177 offset:56320
	global_load_lds_dwordx4 v[222:223], off
	s_add_i32 m0, s30, 0x2000
	s_add_u32 s28, s28, 0x80080
	v_lshl_add_u64 v[222:223], v[224:225], 0, s[8:9]
	s_addc_u32 s29, s29, 0
	s_add_i32 s30, s68, s33
	global_load_lds_dwordx4 v[222:223], off
	v_lshl_add_u64 v[222:223], s[28:29], 0, v[152:153]
	s_mov_b32 m0, s30
	s_nop 0
	global_load_lds_dwordx4 v[222:223], off
	v_lshl_add_u64 v[222:223], s[28:29], 0, v[148:149]
	s_add_i32 m0, s30, 0x2000
	s_nop 0
	global_load_lds_dwordx4 v[222:223], off
	v_lshl_add_u64 v[222:223], v[226:227], 0, s[8:9]
	s_mov_b32 m0, s41
	s_nop 0
	global_load_lds_dwordx4 v[222:223], off
	v_lshl_add_u64 v[222:223], v[228:229], 0, s[8:9]
	s_mov_b32 m0, s42
	s_nop 0
	global_load_lds_dwordx4 v[222:223], off
	s_waitcnt vmcnt(8)
	s_waitcnt lgkmcnt(0)
	s_setprio 1
	s_barrier
	v_mfma_f32_16x16x32_bf16 v[62:65], v[98:101], v[190:193], v[62:65]
	v_mfma_f32_16x16x32_bf16 v[58:61], v[106:109], v[190:193], v[58:61]
	v_mfma_f32_16x16x32_bf16 v[46:49], v[98:101], v[198:201], v[46:49]
	v_mfma_f32_16x16x32_bf16 v[42:45], v[106:109], v[198:201], v[42:45]
	v_mfma_f32_16x16x32_bf16 v[30:33], v[98:101], v[206:209], v[30:33]
	v_mfma_f32_16x16x32_bf16 v[26:29], v[106:109], v[206:209], v[26:29]
	v_mfma_f32_16x16x32_bf16 v[14:17], v[98:101], v[214:217], v[14:17]
	v_mfma_f32_16x16x32_bf16 v[10:13], v[106:109], v[214:217], v[10:13]
	v_mfma_f32_16x16x32_bf16 v[62:65], v[102:105], v[194:197], v[62:65]
	v_mfma_f32_16x16x32_bf16 v[58:61], v[110:113], v[194:197], v[58:61]
	v_mfma_f32_16x16x32_bf16 v[46:49], v[102:105], v[202:205], v[46:49]
	v_mfma_f32_16x16x32_bf16 v[42:45], v[110:113], v[202:205], v[42:45]
	v_mfma_f32_16x16x32_bf16 v[30:33], v[102:105], v[210:213], v[30:33]
	v_mfma_f32_16x16x32_bf16 v[26:29], v[110:113], v[210:213], v[26:29]
	v_mfma_f32_16x16x32_bf16 v[14:17], v[102:105], v[218:221], v[14:17]
	v_mfma_f32_16x16x32_bf16 v[10:13], v[110:113], v[218:221], v[10:13]
	v_mfma_f32_16x16x32_bf16 v[54:57], v[164:167], v[190:193], v[54:57]
	v_mfma_f32_16x16x32_bf16 v[50:53], v[182:185], v[190:193], v[50:53]
	v_mfma_f32_16x16x32_bf16 v[38:41], v[164:167], v[198:201], v[38:41]
	v_mfma_f32_16x16x32_bf16 v[34:37], v[182:185], v[198:201], v[34:37]
	v_mfma_f32_16x16x32_bf16 v[22:25], v[164:167], v[206:209], v[22:25]
	v_mfma_f32_16x16x32_bf16 v[18:21], v[182:185], v[206:209], v[18:21]
	v_mfma_f32_16x16x32_bf16 v[6:9], v[164:167], v[214:217], v[6:9]
	v_mfma_f32_16x16x32_bf16 v[2:5], v[182:185], v[214:217], v[2:5]
	v_mfma_f32_16x16x32_bf16 v[54:57], v[168:171], v[194:197], v[54:57]
	v_mfma_f32_16x16x32_bf16 v[50:53], v[186:189], v[194:197], v[50:53]
	v_mfma_f32_16x16x32_bf16 v[38:41], v[168:171], v[202:205], v[38:41]
	v_mfma_f32_16x16x32_bf16 v[34:37], v[186:189], v[202:205], v[34:37]
	v_mfma_f32_16x16x32_bf16 v[22:25], v[168:171], v[210:213], v[22:25]
	v_mfma_f32_16x16x32_bf16 v[18:21], v[186:189], v[210:213], v[18:21]
	v_mfma_f32_16x16x32_bf16 v[6:9], v[168:171], v[218:221], v[6:9]
	v_mfma_f32_16x16x32_bf16 v[2:5], v[186:189], v[218:221], v[2:5]
	s_barrier
	s_setprio 0
	s_add_i32 s58, s58, 2
	s_add_u32 s26, s26, 0x100
	s_addc_u32 s27, s27, 0
	s_add_u32 s56, s56, 0x100
	s_addc_u32 s57, s57, 0
	s_cmp_gt_u32 s58, 29
	s_cbranch_scc0 .LBB0_1208
	s_and_b64 vcc, exec, s[16:17]
	s_cbranch_vccz .LBB0_1211
	s_barrier

.LBB0_1284:
	ds_read_b128 v[122:125], v173
	ds_read_b128 v[126:129], v173 offset:1024
	ds_read_b128 v[130:133], v173 offset:2048
	ds_read_b128 v[134:137], v173 offset:3072
	ds_read_b128 v[164:167], v174
	ds_read_b128 v[180:183], v174 offset:1024
	ds_read_b128 v[184:187], v174 offset:2048
	ds_read_b128 v[188:191], v174 offset:3072
	s_add_u32 s28, s26, 0x100
	s_addc_u32 s29, s27, 0
	s_cmpk_eq_i32 s60, 0x54
	s_cselect_b32 s35, s5, s29
	s_cselect_b32 s34, s4, s28
	s_cselect_b32 s31, s25, s59
	s_cselect_b32 s30, s24, s58
	v_lshl_add_u64 v[168:169], s[26:27], 0, v[156:157]
	s_add_i32 m0, s38, 0xc000
	ds_read_b128 v[192:195], v175
	ds_read_b128 v[196:199], v175 offset:1024
	ds_read_b128 v[200:203], v175 offset:2048
	ds_read_b128 v[204:207], v175 offset:3072
	ds_read_b128 v[208:211], v175 offset:4096
	ds_read_b128 v[212:215], v175 offset:5120
	ds_read_b128 v[216:219], v175 offset:6144
	ds_read_b128 v[220:223], v175 offset:7168
	global_load_lds_dwordx4 v[168:169], off
	v_lshl_add_u64 v[168:169], s[26:27], 0, v[158:159]
	s_add_i32 m0, s38, 0xe000
	s_nop 0
	global_load_lds_dwordx4 v[168:169], off
	s_waitcnt vmcnt(8)
	s_waitcnt lgkmcnt(0)
	s_setprio 1
	s_barrier
	v_mfma_f32_16x16x32_bf16 v[142:145], v[122:125], v[192:195], v[142:145]
	v_mfma_f32_16x16x32_bf16 v[138:141], v[130:133], v[192:195], v[138:141]
	v_mfma_f32_16x16x32_bf16 v[110:113], v[122:125], v[200:203], v[110:113]
	v_mfma_f32_16x16x32_bf16 v[106:109], v[130:133], v[200:203], v[106:109]
	v_mfma_f32_16x16x32_bf16 v[94:97], v[122:125], v[208:211], v[94:97]
	v_mfma_f32_16x16x32_bf16 v[90:93], v[130:133], v[208:211], v[90:93]
	v_mfma_f32_16x16x32_bf16 v[78:81], v[122:125], v[216:219], v[78:81]
	v_mfma_f32_16x16x32_bf16 v[74:77], v[130:133], v[216:219], v[74:77]
	v_mfma_f32_16x16x32_bf16 v[142:145], v[126:129], v[196:199], v[142:145]
	v_mfma_f32_16x16x32_bf16 v[138:141], v[134:137], v[196:199], v[138:141]
	v_mfma_f32_16x16x32_bf16 v[110:113], v[126:129], v[204:207], v[110:113]
	v_mfma_f32_16x16x32_bf16 v[106:109], v[134:137], v[204:207], v[106:109]
	v_mfma_f32_16x16x32_bf16 v[94:97], v[126:129], v[212:215], v[94:97]
	v_mfma_f32_16x16x32_bf16 v[90:93], v[134:137], v[212:215], v[90:93]
	v_mfma_f32_16x16x32_bf16 v[78:81], v[126:129], v[220:223], v[78:81]
	v_mfma_f32_16x16x32_bf16 v[74:77], v[134:137], v[220:223], v[74:77]
	v_mfma_f32_16x16x32_bf16 v[118:121], v[164:167], v[192:195], v[118:121]
	v_mfma_f32_16x16x32_bf16 v[114:117], v[184:187], v[192:195], v[114:117]
	v_mfma_f32_16x16x32_bf16 v[102:105], v[164:167], v[200:203], v[102:105]
	v_mfma_f32_16x16x32_bf16 v[98:101], v[184:187], v[200:203], v[98:101]
	v_mfma_f32_16x16x32_bf16 v[86:89], v[164:167], v[208:211], v[86:89]
	v_mfma_f32_16x16x32_bf16 v[82:85], v[184:187], v[208:211], v[82:85]
	v_mfma_f32_16x16x32_bf16 v[70:73], v[164:167], v[216:219], v[70:73]
	v_mfma_f32_16x16x32_bf16 v[66:69], v[184:187], v[216:219], v[66:69]
	v_mfma_f32_16x16x32_bf16 v[118:121], v[180:183], v[196:199], v[118:121]
	v_mfma_f32_16x16x32_bf16 v[114:117], v[188:191], v[196:199], v[114:117]
	v_mfma_f32_16x16x32_bf16 v[102:105], v[180:183], v[204:207], v[102:105]
	v_mfma_f32_16x16x32_bf16 v[98:101], v[188:191], v[204:207], v[98:101]
	v_mfma_f32_16x16x32_bf16 v[86:89], v[180:183], v[212:215], v[86:89]
	v_mfma_f32_16x16x32_bf16 v[82:85], v[188:191], v[212:215], v[82:85]
	v_mfma_f32_16x16x32_bf16 v[70:73], v[180:183], v[220:223], v[70:73]
	v_mfma_f32_16x16x32_bf16 v[66:69], v[188:191], v[220:223], v[66:69]
	s_barrier
	s_setprio 0
	s_add_i32 s26, s48, s33
	v_lshl_add_u64 v[168:169], s[30:31], 0, v[152:153]
	s_mov_b32 m0, s26
	ds_read_b128 v[192:195], v175 offset:16384
	ds_read_b128 v[196:199], v175 offset:17408
	ds_read_b128 v[200:203], v175 offset:18432
	ds_read_b128 v[204:207], v175 offset:19456
	ds_read_b128 v[208:211], v175 offset:20480
	ds_read_b128 v[212:215], v175 offset:21504
	ds_read_b128 v[216:219], v175 offset:22528
	ds_read_b128 v[220:223], v175 offset:23552
	global_load_lds_dwordx4 v[168:169], off
	s_add_i32 m0, s26, 0x2000
	s_add_u32 s26, s30, 0x160000
	v_lshl_add_u64 v[176:177], s[30:31], 0, v[148:149]
	s_addc_u32 s27, s31, 0
	s_add_i32 s61, s49, s33
	global_load_lds_dwordx4 v[176:177], off
	v_lshl_add_u64 v[224:225], s[26:27], 0, v[152:153]
	s_mov_b32 m0, s61
	v_lshl_add_u64 v[226:227], s[34:35], 0, v[150:151]
	global_load_lds_dwordx4 v[224:225], off
	v_lshl_add_u64 v[224:225], s[26:27], 0, v[148:149]
	s_add_i32 m0, s61, 0x2000
	s_nop 0
	global_load_lds_dwordx4 v[224:225], off
	v_lshl_add_u64 v[224:225], s[34:35], 0, v[154:155]
	s_mov_b32 m0, s38
	s_nop 0
	global_load_lds_dwordx4 v[224:225], off
	s_mov_b32 m0, s39
	s_nop 0
	global_load_lds_dwordx4 v[226:227], off
	s_waitcnt vmcnt(8)
	s_waitcnt lgkmcnt(0)
	s_setprio 1
	s_barrier
	v_mfma_f32_16x16x32_bf16 v[62:65], v[122:125], v[192:195], v[62:65]
	v_mfma_f32_16x16x32_bf16 v[58:61], v[130:133], v[192:195], v[58:61]
	v_mfma_f32_16x16x32_bf16 v[46:49], v[122:125], v[200:203], v[46:49]
	v_mfma_f32_16x16x32_bf16 v[42:45], v[130:133], v[200:203], v[42:45]
	v_mfma_f32_16x16x32_bf16 v[30:33], v[122:125], v[208:211], v[30:33]
	v_mfma_f32_16x16x32_bf16 v[26:29], v[130:133], v[208:211], v[26:29]
	v_mfma_f32_16x16x32_bf16 v[14:17], v[122:125], v[216:219], v[14:17]
	v_mfma_f32_16x16x32_bf16 v[10:13], v[130:133], v[216:219], v[10:13]
	v_mfma_f32_16x16x32_bf16 v[62:65], v[126:129], v[196:199], v[62:65]
	v_mfma_f32_16x16x32_bf16 v[58:61], v[134:137], v[196:199], v[58:61]
	v_mfma_f32_16x16x32_bf16 v[46:49], v[126:129], v[204:207], v[46:49]
	v_mfma_f32_16x16x32_bf16 v[42:45], v[134:137], v[204:207], v[42:45]
	v_mfma_f32_16x16x32_bf16 v[30:33], v[126:129], v[212:215], v[30:33]
	v_mfma_f32_16x16x32_bf16 v[26:29], v[134:137], v[212:215], v[26:29]
	v_mfma_f32_16x16x32_bf16 v[14:17], v[126:129], v[220:223], v[14:17]
	v_mfma_f32_16x16x32_bf16 v[10:13], v[134:137], v[220:223], v[10:13]
	v_mfma_f32_16x16x32_bf16 v[54:57], v[164:167], v[192:195], v[54:57]
	v_mfma_f32_16x16x32_bf16 v[50:53], v[184:187], v[192:195], v[50:53]
	v_mfma_f32_16x16x32_bf16 v[38:41], v[164:167], v[200:203], v[38:41]
	v_mfma_f32_16x16x32_bf16 v[34:37], v[184:187], v[200:203], v[34:37]
	v_mfma_f32_16x16x32_bf16 v[22:25], v[164:167], v[208:211], v[22:25]
	v_mfma_f32_16x16x32_bf16 v[18:21], v[184:187], v[208:211], v[18:21]
	v_mfma_f32_16x16x32_bf16 v[6:9], v[164:167], v[216:219], v[6:9]
	v_mfma_f32_16x16x32_bf16 v[2:5], v[184:187], v[216:219], v[2:5]
	v_mfma_f32_16x16x32_bf16 v[54:57], v[180:183], v[196:199], v[54:57]
	v_mfma_f32_16x16x32_bf16 v[50:53], v[188:191], v[196:199], v[50:53]
	v_mfma_f32_16x16x32_bf16 v[38:41], v[180:183], v[204:207], v[38:41]
	v_mfma_f32_16x16x32_bf16 v[34:37], v[188:191], v[204:207], v[34:37]
	v_mfma_f32_16x16x32_bf16 v[22:25], v[180:183], v[212:215], v[22:25]
	v_mfma_f32_16x16x32_bf16 v[18:21], v[188:191], v[212:215], v[18:21]
	v_mfma_f32_16x16x32_bf16 v[6:9], v[180:183], v[220:223], v[6:9]
	v_mfma_f32_16x16x32_bf16 v[2:5], v[188:191], v[220:223], v[2:5]
	s_barrier
	s_setprio 0
	s_add_i32 s61, 0, 0x18000
	s_add_i32 s68, 0, 0x1c000
	v_add_u32_e32 v134, s61, v171
	v_add_u32_e32 v179, s68, v171
	ds_read_b128 v[122:125], v134
	ds_read_b128 v[126:129], v134 offset:1024
	ds_read_b128 v[130:133], v134 offset:2048
	ds_read_b128 v[134:137], v134 offset:3072
	ds_read_b128 v[164:167], v179
	ds_read_b128 v[180:183], v179 offset:1024
	ds_read_b128 v[184:187], v179 offset:2048
	ds_read_b128 v[188:191], v179 offset:3072
	s_add_u32 s26, s34, 0x160000
	s_addc_u32 s27, s35, 0
	s_mov_b32 m0, s40
	v_lshl_add_u64 v[228:229], s[26:27], 0, v[154:155]
	ds_read_b128 v[192:195], v175 offset:32768
	ds_read_b128 v[196:199], v175 offset:33792
	ds_read_b128 v[200:203], v175 offset:34816
	ds_read_b128 v[204:207], v175 offset:35840
	ds_read_b128 v[208:211], v175 offset:36864
	ds_read_b128 v[212:215], v175 offset:37888
	ds_read_b128 v[216:219], v175 offset:38912
	ds_read_b128 v[220:223], v175 offset:39936
	global_load_lds_dwordx4 v[228:229], off
	v_lshl_add_u64 v[228:229], s[26:27], 0, v[150:151]
	s_mov_b32 m0, s41
	s_nop 0
	global_load_lds_dwordx4 v[228:229], off
	s_waitcnt vmcnt(8)
	s_waitcnt lgkmcnt(0)
	s_setprio 1
	s_barrier
	v_mfma_f32_16x16x32_bf16 v[142:145], v[122:125], v[192:195], v[142:145]
	v_mfma_f32_16x16x32_bf16 v[138:141], v[130:133], v[192:195], v[138:141]
	v_mfma_f32_16x16x32_bf16 v[110:113], v[122:125], v[200:203], v[110:113]
	v_mfma_f32_16x16x32_bf16 v[106:109], v[130:133], v[200:203], v[106:109]
	v_mfma_f32_16x16x32_bf16 v[94:97], v[122:125], v[208:211], v[94:97]
	v_mfma_f32_16x16x32_bf16 v[90:93], v[130:133], v[208:211], v[90:93]
	v_mfma_f32_16x16x32_bf16 v[78:81], v[122:125], v[216:219], v[78:81]
	v_mfma_f32_16x16x32_bf16 v[74:77], v[130:133], v[216:219], v[74:77]
	v_mfma_f32_16x16x32_bf16 v[142:145], v[126:129], v[196:199], v[142:145]
	v_mfma_f32_16x16x32_bf16 v[138:141], v[134:137], v[196:199], v[138:141]
	v_mfma_f32_16x16x32_bf16 v[110:113], v[126:129], v[204:207], v[110:113]
	v_mfma_f32_16x16x32_bf16 v[106:109], v[134:137], v[204:207], v[106:109]
	v_mfma_f32_16x16x32_bf16 v[94:97], v[126:129], v[212:215], v[94:97]
	v_mfma_f32_16x16x32_bf16 v[90:93], v[134:137], v[212:215], v[90:93]
	v_mfma_f32_16x16x32_bf16 v[78:81], v[126:129], v[220:223], v[78:81]
	v_mfma_f32_16x16x32_bf16 v[74:77], v[134:137], v[220:223], v[74:77]
	v_mfma_f32_16x16x32_bf16 v[118:121], v[164:167], v[192:195], v[118:121]
	v_mfma_f32_16x16x32_bf16 v[114:117], v[184:187], v[192:195], v[114:117]
	v_mfma_f32_16x16x32_bf16 v[102:105], v[164:167], v[200:203], v[102:105]
	v_mfma_f32_16x16x32_bf16 v[98:101], v[184:187], v[200:203], v[98:101]
	v_mfma_f32_16x16x32_bf16 v[86:89], v[164:167], v[208:211], v[86:89]
	v_mfma_f32_16x16x32_bf16 v[82:85], v[184:187], v[208:211], v[82:85]
	v_mfma_f32_16x16x32_bf16 v[70:73], v[164:167], v[216:219], v[70:73]
	v_mfma_f32_16x16x32_bf16 v[66:69], v[184:187], v[216:219], v[66:69]
	v_mfma_f32_16x16x32_bf16 v[118:121], v[180:183], v[196:199], v[118:121]
	v_mfma_f32_16x16x32_bf16 v[114:117], v[188:191], v[196:199], v[114:117]
	v_mfma_f32_16x16x32_bf16 v[102:105], v[180:183], v[204:207], v[102:105]
	v_mfma_f32_16x16x32_bf16 v[98:101], v[188:191], v[204:207], v[98:101]
	v_mfma_f32_16x16x32_bf16 v[86:89], v[180:183], v[212:215], v[86:89]
	v_mfma_f32_16x16x32_bf16 v[82:85], v[188:191], v[212:215], v[82:85]
	v_mfma_f32_16x16x32_bf16 v[70:73], v[180:183], v[220:223], v[70:73]
	v_mfma_f32_16x16x32_bf16 v[66:69], v[188:191], v[220:223], v[66:69]
	s_barrier
	s_setprio 0
	s_add_i32 s26, s61, s33
	v_lshl_add_u64 v[168:169], v[168:169], 0, s[8:9]
	s_mov_b32 m0, s26
	ds_read_b128 v[192:195], v175 offset:49152
	ds_read_b128 v[196:199], v175 offset:50176
	ds_read_b128 v[200:203], v175 offset:51200
	ds_read_b128 v[204:207], v175 offset:52224
	ds_read_b128 v[208:211], v175 offset:53248
	ds_read_b128 v[212:215], v175 offset:54272
	ds_read_b128 v[216:219], v175 offset:55296
	ds_read_b128 v[220:223], v175 offset:56320
	global_load_lds_dwordx4 v[168:169], off
	s_add_i32 m0, s26, 0x2000
	s_add_u32 s26, s30, 0x160080
	v_lshl_add_u64 v[168:169], v[176:177], 0, s[8:9]
	s_addc_u32 s27, s31, 0
	s_add_i32 s30, s68, s33
	global_load_lds_dwordx4 v[168:169], off
	v_lshl_add_u64 v[168:169], s[26:27], 0, v[152:153]
	s_mov_b32 m0, s30
	s_nop 0
	global_load_lds_dwordx4 v[168:169], off
	v_lshl_add_u64 v[168:169], s[26:27], 0, v[148:149]
	s_add_i32 m0, s30, 0x2000
	s_nop 0
	global_load_lds_dwordx4 v[168:169], off
	v_lshl_add_u64 v[168:169], v[224:225], 0, s[8:9]
	s_mov_b32 m0, s43
	s_nop 0
	global_load_lds_dwordx4 v[168:169], off
	v_lshl_add_u64 v[168:169], v[226:227], 0, s[8:9]
	s_mov_b32 m0, s44
	s_nop 0
	global_load_lds_dwordx4 v[168:169], off
	s_waitcnt vmcnt(8)
	s_waitcnt lgkmcnt(0)
	s_setprio 1
	s_barrier
	v_mfma_f32_16x16x32_bf16 v[62:65], v[122:125], v[192:195], v[62:65]
	v_mfma_f32_16x16x32_bf16 v[58:61], v[130:133], v[192:195], v[58:61]
	v_mfma_f32_16x16x32_bf16 v[46:49], v[122:125], v[200:203], v[46:49]
	v_mfma_f32_16x16x32_bf16 v[42:45], v[130:133], v[200:203], v[42:45]
	v_mfma_f32_16x16x32_bf16 v[30:33], v[122:125], v[208:211], v[30:33]
	v_mfma_f32_16x16x32_bf16 v[26:29], v[130:133], v[208:211], v[26:29]
	v_mfma_f32_16x16x32_bf16 v[14:17], v[122:125], v[216:219], v[14:17]
	v_mfma_f32_16x16x32_bf16 v[10:13], v[130:133], v[216:219], v[10:13]
	v_mfma_f32_16x16x32_bf16 v[62:65], v[126:129], v[196:199], v[62:65]
	v_mfma_f32_16x16x32_bf16 v[58:61], v[134:137], v[196:199], v[58:61]
	v_mfma_f32_16x16x32_bf16 v[46:49], v[126:129], v[204:207], v[46:49]
	v_mfma_f32_16x16x32_bf16 v[42:45], v[134:137], v[204:207], v[42:45]
	v_mfma_f32_16x16x32_bf16 v[30:33], v[126:129], v[212:215], v[30:33]
	v_mfma_f32_16x16x32_bf16 v[26:29], v[134:137], v[212:215], v[26:29]
	v_mfma_f32_16x16x32_bf16 v[14:17], v[126:129], v[220:223], v[14:17]
	v_mfma_f32_16x16x32_bf16 v[10:13], v[134:137], v[220:223], v[10:13]
	v_mfma_f32_16x16x32_bf16 v[54:57], v[164:167], v[192:195], v[54:57]
	v_mfma_f32_16x16x32_bf16 v[50:53], v[184:187], v[192:195], v[50:53]
	v_mfma_f32_16x16x32_bf16 v[38:41], v[164:167], v[200:203], v[38:41]
	v_mfma_f32_16x16x32_bf16 v[34:37], v[184:187], v[200:203], v[34:37]
	v_mfma_f32_16x16x32_bf16 v[22:25], v[164:167], v[208:211], v[22:25]
	v_mfma_f32_16x16x32_bf16 v[18:21], v[184:187], v[208:211], v[18:21]
	v_mfma_f32_16x16x32_bf16 v[6:9], v[164:167], v[216:219], v[6:9]
	v_mfma_f32_16x16x32_bf16 v[2:5], v[184:187], v[216:219], v[2:5]
	v_mfma_f32_16x16x32_bf16 v[54:57], v[180:183], v[196:199], v[54:57]
	v_mfma_f32_16x16x32_bf16 v[50:53], v[188:191], v[196:199], v[50:53]
	v_mfma_f32_16x16x32_bf16 v[38:41], v[180:183], v[204:207], v[38:41]
	v_mfma_f32_16x16x32_bf16 v[34:37], v[188:191], v[204:207], v[34:37]
	v_mfma_f32_16x16x32_bf16 v[22:25], v[180:183], v[212:215], v[22:25]
	v_mfma_f32_16x16x32_bf16 v[18:21], v[188:191], v[212:215], v[18:21]
	v_mfma_f32_16x16x32_bf16 v[6:9], v[180:183], v[220:223], v[6:9]
	v_mfma_f32_16x16x32_bf16 v[2:5], v[188:191], v[220:223], v[2:5]
	s_barrier
	s_setprio 0
	s_add_i32 s60, s60, 2
	s_add_u32 s58, s58, 0x100
	s_addc_u32 s59, s59, 0
	s_cmpk_gt_u32 s60, 0x55
	s_mov_b64 s[26:27], s[28:29]
	s_cbranch_scc0 .LBB0_1284
	s_and_b64 vcc, exec, s[12:13]
	s_cbranch_vccz .LBB0_1287
	s_barrier
